# cmp_attn: top-16 rank loops use 64-bit (ordered-score,index) keys with v_cmp_gt_u64; importance accumulation pipelined per half-wave (same add order); phase starts 256B-aligned
# speedup vs baseline: 1.0059x; 1.0059x over previous
.LBB0_332:
	s_or_b64 exec, exec, s[2:3]
	s_mov_b64 s[10:11], s[58:59]
	v_readlane_b32 s2, v254, 0
	s_barrier
	.p2align 8
	s_and_b32 s4, 0xffff, s2
	s_load_dwordx2 s[2:3], s[10:11], 0x58
	s_load_dwordx2 s[6:7], s[10:11], 0xe0
	v_mov_b32_e32 v0, v208
	s_mul_i32 s5, s92, s4
	s_mul_i32 s4, s94, s4
	v_add_u32_e32 v0, s5, v0
	s_mov_b32 s5, 0xc000
	v_cmp_gt_i32_e32 vcc, s5, v0
	s_and_saveexec_b64 s[8:9], vcc
	v_readlane_b32 s35, v254, 2
	s_cbranch_execz .LBB0_337
	s_load_dwordx2 s[10:11], s[10:11], 0x20
	s_waitcnt lgkmcnt(0)
	s_add_u32 s12, s6, 0x9aa0000
	s_addc_u32 s13, s7, 0
	s_mov_b64 s[14:15], 0
	s_mov_b32 s18, 0x2aaaaaab
	s_movk_i32 s19, 0x1800
	s_mov_b32 s20, 0xbfff
	v_mov_b32_e32 v2, v0

.LBB0_392:
	s_or_b64 exec, exec, s[2:3]
	s_mul_i32 s2, s95, s94
	s_lshl_b32 s86, s94, 2
	s_lshl_b32 s3, s92, 2
	s_mul_i32 s49, s2, s35
	s_add_u32 s2, s0, 0x271e8a00
	v_writelane_b32 v254, s3, 21
	s_addc_u32 s3, s1, 0
	s_add_u32 s76, s0, 0x271e8c00
	v_writelane_b32 v254, s2, 22
	s_addc_u32 s77, s1, 0
	v_mbcnt_lo_u32_b32 v1, -1, 0
	v_writelane_b32 v254, s3, 23
	s_add_u32 s2, s0, 0x271e8d00
	s_addc_u32 s3, s1, 0
	v_writelane_b32 v254, s2, 15
	v_mbcnt_hi_u32_b32 v215, -1, v1
	v_and_b32_e32 v1, 64, v215
	v_writelane_b32 v254, s3, 16
	s_add_u32 s2, s0, 0x271e8e00
	s_addc_u32 s3, s1, 0
	v_writelane_b32 v254, s2, 2
	s_mov_b32 s85, 0
	s_movk_i32 s35, 0x80
	v_writelane_b32 v254, s3, 3
	s_add_u32 s2, s0, 0x271e8f00
	s_addc_u32 s3, s1, 0
	v_writelane_b32 v254, s2, 0
	s_movk_i32 s25, 0x180
	s_movk_i32 s33, 0x6000
	v_writelane_b32 v254, s3, 1
	s_add_u32 s2, s0, 0x271e9000
	s_addc_u32 s3, s1, 0
	v_writelane_b32 v254, s2, 6
	s_movk_i32 s50, 0x4000
	s_waitcnt lgkmcnt(0)
	v_mov_b32_e32 v0, 0
	v_writelane_b32 v254, s3, 7
	s_add_u32 s2, s0, 0x271e9100
	s_addc_u32 s3, s1, 0
	v_writelane_b32 v254, s2, 17
	s_movk_i32 s51, 0x200
	s_movk_i32 s68, 0x3fff
	v_writelane_b32 v254, s3, 18
	s_add_u32 s2, s0, 0x271e9200
	s_addc_u32 s3, s1, 0
	v_writelane_b32 v254, s2, 13
	v_mov_b32_e32 v209, 0x358637bd
	s_mov_b32 s52, 0x800000
	v_writelane_b32 v254, s3, 14
	s_add_u32 s2, s0, 0x271e9300
	s_addc_u32 s3, s1, 0
	v_writelane_b32 v254, s2, 19
	s_movk_i32 s53, 0xff
	v_mov_b32_e32 v214, 1
	v_writelane_b32 v254, s3, 20
	s_add_u32 s2, s0, 0x271e9400
	s_addc_u32 s3, s1, 0
	v_writelane_b32 v254, s2, 24
	s_movk_i32 s45, 0x70
	s_mov_b32 s55, 0x3fffffc0
	v_writelane_b32 v254, s3, 25
	s_add_u32 s2, s0, 0x271e9500
	s_addc_u32 s3, s1, 0
	v_writelane_b32 v254, s2, 26
	s_movk_i32 s56, 0x204
	v_xor_b32_e32 v216, 16, v215
	v_writelane_b32 v254, s3, 27
	s_add_u32 s2, s0, 0x271e9600
	s_addc_u32 s3, s1, 0
	v_writelane_b32 v254, s2, 28
	v_add_u32_e32 v217, 64, v1
	v_mov_b32_e32 v218, 0x10200
	v_writelane_b32 v254, s3, 29
	s_add_u32 s2, s0, 0x271e9700
	s_addc_u32 s3, s1, 0
	v_writelane_b32 v254, s2, 30
	v_mov_b32_e32 v219, 0x80
	v_mov_b32_e32 v220, 0x41b17218
	v_writelane_b32 v254, s3, 31
	s_add_u32 s2, s0, 0x271e9800
	s_addc_u32 s3, s1, 0
	v_writelane_b32 v254, s2, 32
	v_mov_b32_e32 v221, 0xff800000
	s_mov_b32 s48, 0x3f317217
	v_writelane_b32 v254, s3, 33
	s_add_u32 s2, s0, 0x271e9900
	s_addc_u32 s3, s1, 0
	v_writelane_b32 v254, s2, 34
	s_movk_i32 s61, 0x2000
	s_movk_i32 s97, 0x110
	v_writelane_b32 v254, s3, 35
	s_add_u32 s2, s0, 0x271e9a00
	s_addc_u32 s3, s1, 0
	v_writelane_b32 v254, s2, 36
	s_mov_b32 s64, 0xff800000
	s_movk_i32 s65, 0x1ff
	v_writelane_b32 v254, s3, 37
	s_add_u32 s2, s0, 0x271e9b00
	s_addc_u32 s3, s1, 0
	v_writelane_b32 v254, s2, 38
	s_mov_b32 s67, 0xc000
	s_movk_i32 s69, 0x7f
	v_writelane_b32 v254, s3, 39
	s_add_u32 s2, s0, 0x271ebc00
	s_addc_u32 s3, s1, 0
	v_writelane_b32 v254, s2, 40
	s_add_u32 s0, s0, 0x271ebd00
	s_addc_u32 s1, s1, 0
	v_writelane_b32 v254, s3, 41
	v_writelane_b32 v254, s0, 42
	s_cmpk_lt_i32 s92, 0x800
	s_movk_i32 s71, 0x9f
	v_writelane_b32 v254, s1, 43
	s_cselect_b64 s[0:1], -1, 0
	v_writelane_b32 v254, s0, 44
	s_cmpk_lt_i32 s92, 0x80
	s_movk_i32 s72, 0xaf
	v_writelane_b32 v254, s1, 45
	s_cselect_b64 s[0:1], -1, 0
	v_writelane_b32 v254, s0, 46
	s_movk_i32 s73, 0x10f
	s_movk_i32 s54, 0x11f
	v_writelane_b32 v254, s1, 47
	s_not_b32 s0, s92
	s_add_i32 s57, s94, s0
	s_cmpk_lt_i32 s92, 0x600
	s_cselect_b64 s[0:1], -1, 0
	v_writelane_b32 v254, s0, 48
	s_cmpk_lt_i32 s92, 0x180
	s_movk_i32 s63, 0x12f
	v_writelane_b32 v254, s1, 49
	s_cselect_b64 s[0:1], -1, 0
	v_writelane_b32 v254, s0, 50
	s_cmp_lt_i32 s92, 64
	s_movk_i32 s80, 0x18f
	v_writelane_b32 v254, s1, 51
	s_cselect_b64 s[0:1], -1, 0
	v_writelane_b32 v254, s0, 52
	s_cmp_lt_i32 s92, 32
	s_movk_i32 s81, 0x19f
	v_writelane_b32 v254, s1, 53
	s_cselect_b64 s[0:1], -1, 0
	v_writelane_b32 v254, s0, 54
	s_cmpk_lt_i32 s92, 0x400
	s_movk_i32 s62, 0x1af
	v_writelane_b32 v254, s1, 55
	s_cselect_b64 s[0:1], -1, 0
	v_writelane_b32 v254, s0, 56
	s_cmpk_lt_i32 s92, 0x1080
	s_mov_b64 s[88:89], 0x80
	v_writelane_b32 v254, s1, 57
	s_cselect_b64 s[0:1], -1, 0
	v_writelane_b32 v254, s0, 58
	s_ashr_i32 s87, s86, 31
	s_mov_b64 s[78:79], 0x4000
	v_writelane_b32 v254, s1, 59
	s_lshl_b64 s[0:1], s[86:87], 12
	v_writelane_b32 v254, s0, 60
	s_mov_b32 s87, 0x1ffffc0
	s_mov_b64 s[82:83], 0x100
	v_writelane_b32 v254, s1, 61
	s_lshl_b32 s0, s92, 3
	v_writelane_b32 v254, s0, 62
	s_lshl_b32 s0, s94, 3
	v_writelane_b32 v254, s0, 63
	s_lshl_b32 s0, s92, 7
	v_writelane_b32 v255, s0, 0
	s_lshl_b32 s0, s94, 7
	v_writelane_b32 v255, s0, 1
	s_lshl_b32 s0, s92, 6
	v_writelane_b32 v255, s0, 2
	s_lshl_b32 s0, s94, 6
	s_bitcmp1_b32 s92, 0
	v_writelane_b32 v255, s0, 3
	s_cselect_b64 s[0:1], -1, 0
	v_writelane_b32 v255, s0, 4
	s_bitcmp1_b32 s94, 0
	s_mov_b64 s[74:75], 0x60
	v_writelane_b32 v255, s1, 5
	s_cselect_b64 s[0:1], -1, 0
	v_writelane_b32 v255, s0, 6
	s_lshl_b32 s60, s94, 8
	s_lshl_b32 s66, s94, 4
	v_writelane_b32 v255, s1, 7
	s_lshl_b32 s0, s92, 8
	v_writelane_b32 v255, s0, 8
	s_lshl_b32 s0, s92, 4
	v_writelane_b32 v255, s0, 9
	s_mov_b64 s[0:1], -1
	v_writelane_b32 v255, s0, 10
	s_mov_b64 s[90:91], 0x180
	s_mov_b32 s96, 0x3dd53b94
	v_writelane_b32 v255, s1, 11
	s_mov_b32 s0, s86
	v_writelane_b32 v255, s0, 12
	s_mov_b64 s[36:37], 0x10000
	s_mov_b32 s4, s85
	v_writelane_b32 v255, s1, 13
	v_writelane_b32 v255, s49, 14
	v_writelane_b32 v255, s76, 15
	s_barrier
	.p2align 8
	s_nop 0
	v_writelane_b32 v255, s77, 16
	v_writelane_b32 v255, s57, 17
	v_writelane_b32 v255, s60, 18
	v_writelane_b32 v255, s66, 19
	s_branch .LBB0_396

.LBB0_394:
	s_or_b64 exec, exec, s[0:1]
	s_mov_b64 s[0:1], 0
	s_waitcnt lgkmcnt(0)
	s_barrier
	.p2align 8

.LBB0_451:
	s_or_b64 exec, exec, s[2:3]
	s_and_b64 vcc, exec, s[0:1]
	v_readlane_b32 s0, v254, 44
	v_readlane_b32 s1, v254, 45
	s_mov_b64 s[2:3], -1
	s_waitcnt lgkmcnt(0)
	v_cndmask_b32_e64 v1, 0, 1, s[0:1]
	v_cmp_ne_u32_e64 s[0:1], 1, v1
	s_barrier
	.p2align 8
	s_nop 0
	v_writelane_b32 v255, s0, 24
	s_nop 1
	v_writelane_b32 v255, s1, 25
	s_cbranch_vccz .LBB0_869
	s_load_dwordx2 s[0:1], s[58:59], 0xe0
	v_readlane_b32 s4, v255, 24
	v_readlane_b32 s5, v255, 25
	s_movk_i32 s93, 0x70
	s_and_b64 vcc, exec, s[4:5]
	s_cbranch_vccnz .LBB0_496
	s_waitcnt lgkmcnt(0)
	s_add_u32 s14, s0, 0x9dd8800
	s_addc_u32 s15, s1, 0
	s_add_u32 s24, s0, 0x1c20000
	s_addc_u32 s34, s1, 0
	s_add_u32 s16, s0, 0x9cd8800
	s_addc_u32 s17, s1, 0
	s_add_u32 s18, s0, 0x9d58800
	s_addc_u32 s19, s1, 0
	s_add_u32 s42, s0, 0x1c20080
	s_addc_u32 s43, s1, 0
	s_add_u32 s20, s0, 0x9dd8880
	s_addc_u32 s21, s1, 0
	s_add_u32 s22, s0, 0x13dd8800
	s_addc_u32 s23, s1, 0
	s_add_u32 s44, s0, 0x12dd8800
	s_load_dwordx2 s[12:13], s[58:59], 0xb0
	s_addc_u32 s45, s1, 0
	s_add_u32 s46, s0, 0x11dd8800
	s_addc_u32 s47, s1, 0
	s_add_u32 s48, s0, 0xddd8800
	s_addc_u32 s49, s1, 0
	v_readlane_b32 s58, v254, 62
	s_mov_b32 s59, s92
	s_mov_b32 s68, s92
	s_branch .LBB0_455

.LBB0_597:
	s_or_b64 exec, exec, s[0:1]
	s_mov_b64 s[0:1], s[58:59]
	s_waitcnt lgkmcnt(0)
	s_barrier
	.p2align 8
	s_load_dwordx2 s[0:1], s[0:1], 0xe0
	v_mov_b32_e32 v66, v208
	v_mov_b32_e32 v3, v0
	v_lshlrev_b32_e32 v1, 4, v66
	s_waitcnt lgkmcnt(0)
	s_add_u32 s16, s0, 0x15fe8800
	v_and_b32_e32 v2, 0x7f0, v1
	v_bfe_u32 v8, v66, 5, 1
	s_addc_u32 s17, s1, 0
	v_lshl_add_u64 v[4:5], s[0:1], 0, v[2:3]
	s_mov_b64 s[2:3], 0x13dd8800
	s_add_u32 s18, s0, 0x170e8800
	v_lshl_add_u64 v[70:71], v[4:5], 0, s[2:3]
	v_lshlrev_b32_e32 v4, 4, v8
	v_mov_b32_e32 v5, v0
	v_max_i32_e32 v20, 0x100, v66
	s_addc_u32 s19, s1, 0
	s_waitcnt vmcnt(1)
	v_lshl_add_u64 v[6:7], s[0:1], 0, v[4:5]
	s_mov_b64 s[0:1], 0x15dd8800
	v_sub_u32_e32 v20, v20, v66
	v_and_b32_e32 v68, 31, v66
	v_lshl_add_u64 v[72:73], v[6:7], 0, s[0:1]
	s_movk_i32 s0, 0x810
	v_add_u32_e32 v20, 0xff, v20
	v_mad_u32_u24 v69, v68, s0, v4
	v_lshlrev_b32_e32 v4, 2, v8
	v_add_u32_e32 v67, 0x100, v66
	v_add_u32_e32 v6, 0x200, v66
	v_add_u32_e32 v7, 0x300, v66
	v_add_u32_e32 v8, 0x400, v66
	v_add_u32_e32 v9, 0x500, v66
	s_waitcnt vmcnt(0)
	v_add_u32_e32 v10, 0x600, v66
	v_add_u32_e32 v11, 0x700, v66
	v_add_u32_e32 v12, 0x800, v66
	v_add_u32_e32 v13, 0x900, v66
	v_add_u32_e32 v14, 0xa00, v66
	v_add_u32_e32 v15, 0xb00, v66
	v_add_u32_e32 v16, 0xc00, v66
	v_add_u32_e32 v17, 0xd00, v66
	v_add_u32_e32 v18, 0xe00, v66
	v_add_u32_e32 v19, 0xf00, v66
	v_lshrrev_b32_e32 v21, 8, v20
	v_ashrrev_i32_e32 v112, 7, v66
	v_ashrrev_i32_e32 v113, 7, v67
	v_ashrrev_i32_e32 v114, 7, v6
	v_ashrrev_i32_e32 v115, 7, v7
	v_ashrrev_i32_e32 v116, 7, v8
	v_ashrrev_i32_e32 v117, 7, v9
	v_ashrrev_i32_e32 v118, 7, v10
	v_ashrrev_i32_e32 v119, 7, v11
	v_ashrrev_i32_e32 v120, 7, v12
	v_ashrrev_i32_e32 v121, 7, v13
	v_ashrrev_i32_e32 v122, 7, v14
	v_ashrrev_i32_e32 v123, 7, v15
	v_ashrrev_i32_e32 v124, 7, v16
	v_ashrrev_i32_e32 v125, 7, v17
	v_ashrrev_i32_e32 v126, 7, v18
	v_ashrrev_i32_e32 v127, 7, v19
	v_add_u32_e32 v21, 1, v21
	v_ashrrev_i32_e32 v1, 5, v66
	v_mul_lo_u32 v3, v112, s0
	v_mul_lo_u32 v5, v113, s0
	v_mul_lo_u32 v6, v114, s0
	v_mul_lo_u32 v7, v115, s0
	v_mul_lo_u32 v8, v116, s0
	v_mul_lo_u32 v9, v117, s0
	v_mul_lo_u32 v10, v118, s0
	v_mul_lo_u32 v11, v119, s0
	v_mul_lo_u32 v12, v120, s0
	v_mul_lo_u32 v13, v121, s0
	v_mul_lo_u32 v14, v122, s0
	v_mul_lo_u32 v15, v123, s0
	v_mul_lo_u32 v16, v124, s0
	v_mul_lo_u32 v17, v125, s0
	v_mul_lo_u32 v18, v126, s0
	v_mul_lo_u32 v19, v127, s0
	v_and_b32_e32 v128, 0x1fffffe, v21
	v_lshlrev_b32_e32 v130, 2, v66
	v_cmp_gt_i32_e32 vcc, s51, v66
	v_and_b32_e32 v1, -2, v1
	v_cmp_lt_u32_e64 s[4:5], s53, v20
	v_lshl_add_u32 v129, v128, 8, v66
	v_cmp_ne_u32_e64 s[6:7], v21, v128
	v_add_u32_e32 v131, 0x10600, v130
	v_lshl_add_u32 v132, v68, 6, v218
	s_mov_b32 s20, 0
	v_add_u32_e32 v133, v2, v3
	v_add_u32_e32 v134, v2, v5
	v_add_u32_e32 v135, v2, v6
	v_add_u32_e32 v136, v2, v7
	v_add_u32_e32 v137, v2, v8
	v_add_u32_e32 v138, v2, v9
	v_add_u32_e32 v139, v2, v10
	v_add_u32_e32 v140, v2, v11
	v_add_u32_e32 v141, v2, v12
	v_add_u32_e32 v142, v2, v13
	v_add_u32_e32 v143, v2, v14
	v_add_u32_e32 v144, v2, v15
	v_add_u32_e32 v145, v2, v16
	v_add_u32_e32 v146, v2, v17
	v_add_u32_e32 v147, v2, v18
	v_add_u32_e32 v148, v2, v19
	v_lshlrev_b32_e32 v74, 2, v4
	s_mov_b32 s23, s92
	v_readlane_b32 s60, v255, 18
	v_readlane_b32 s66, v255, 19
	s_movk_i32 s68, 0x3fff
	s_mov_b32 s48, 0x3f317217
	s_branch .LBB0_600

.LBB0_670:
	s_or_b64 exec, exec, s[0:1]
	s_mov_b64 s[0:1], s[58:59]
	s_waitcnt lgkmcnt(0)
	s_barrier
	.p2align 8
	v_mov_b32_e32 v1, v208
	s_load_dwordx2 s[0:1], s[0:1], 0xe0
	s_movk_i32 s2, 0x2100
	v_and_b32_e32 v2, 63, v1
	v_ashrrev_i32_e32 v77, 6, v1
	v_mul_lo_u32 v79, v77, s2
	v_lshlrev_b32_e32 v3, 2, v2
	v_or_b32_e32 v4, v79, v3
	s_movk_i32 s2, 0xef00
	v_mad_u64_u32 v[6:7], s[2:3], v77, s2, v[4:5]
	v_and_b32_e32 v5, 1, v77
	s_mov_b32 s4, 0x8080000
	v_mul_lo_u32 v10, v5, s4
	s_movk_i32 s4, 0xffbf
	v_bitop3_b32 v95, v1, s4, 63 bitop3:0x6c
	s_movk_i32 s4, 0xff7f
	v_bitop3_b32 v96, v1, s4, 63 bitop3:0x6c
	s_movk_i32 s4, 0xff3f
	v_bitop3_b32 v97, v1, s4, 63 bitop3:0x6c
	s_movk_i32 s4, 0xfeff
	v_bitop3_b32 v98, v1, s4, 63 bitop3:0x6c
	s_movk_i32 s4, 0xfebf
	v_bitop3_b32 v99, v1, s4, 63 bitop3:0x6c
	s_movk_i32 s4, 0xfe7f
	v_bitop3_b32 v100, v1, s4, 63 bitop3:0x6c
	s_movk_i32 s4, 0xfe3f
	v_bitop3_b32 v101, v1, s4, 63 bitop3:0x6c
	s_movk_i32 s4, 0xfdff
	v_bitop3_b32 v102, v1, s4, 63 bitop3:0x6c
	s_movk_i32 s4, 0xfdbf
	v_bitop3_b32 v103, v1, s4, 63 bitop3:0x6c
	s_movk_i32 s4, 0xfd7f
	v_bitop3_b32 v104, v1, s4, 63 bitop3:0x6c
	s_movk_i32 s4, 0xfd3f
	v_bitop3_b32 v105, v1, s4, 63 bitop3:0x6c
	s_movk_i32 s4, 0xfcff
	s_waitcnt lgkmcnt(0)
	s_add_u32 s2, s0, 0x170e8800
	v_bitop3_b32 v106, v1, s4, 63 bitop3:0x6c
	s_movk_i32 s4, 0xfcbf
	s_addc_u32 s3, s1, 0
	v_mov_b32_e32 v11, v0
	v_bitop3_b32 v107, v1, s4, 63 bitop3:0x6c
	s_movk_i32 s4, 0xfc7f
	v_lshl_add_u64 v[8:9], s[2:3], 0, v[10:11]
	s_add_u32 s0, s0, 0x160e8800
	v_bitop3_b32 v108, v1, s4, 63 bitop3:0x6c
	s_movk_i32 s4, 0xfc3f
	v_or_b32_e32 v10, v10, v3
	v_or_b32_e32 v81, 0x800, v2
	v_lshl_add_u32 v83, v2, 7, v79
	s_addc_u32 s1, s1, 0
	v_lshlrev_b32_e32 v85, 13, v5
	s_mov_b32 s38, 0
	v_cmp_eq_u32_e32 vcc, 0, v2
	v_bitop3_b32 v94, v1, 63, v1 bitop3:0x3f
	v_bitop3_b32 v109, v1, s4, 63 bitop3:0x6c
	v_or_b32_e32 v110, 0x1f80, v2
	v_or_b32_e32 v111, 0x1fc0, v2
	v_cmp_eq_u32_e64 s[4:5], 63, v2
	v_cmp_gt_u32_e64 s[6:7], 62, v2
	v_cmp_gt_u32_e64 s[8:9], 60, v2
	v_cmp_gt_u32_e64 s[10:11], 56, v2
	v_cmp_gt_u32_e64 s[12:13], 48, v2
	v_cmp_gt_u32_e64 s[14:15], 32, v2
	v_lshl_add_u64 v[10:11], s[2:3], 0, v[10:11]
	s_mov_b32 s2, s92
	v_lshl_or_b32 v112, v2, 5, 31
	v_xor_b32_e32 v12, 0xfffff23f, v2
	v_xor_b32_e32 v1, 0xfffff1ff, v2
	v_xor_b32_e32 v14, 0xfffff1bf, v2
	v_xor_b32_e32 v3, 0xfffff17f, v2
	v_xor_b32_e32 v16, 0xfffff13f, v2
	v_xor_b32_e32 v5, 0xfffff0ff, v2
	v_xor_b32_e32 v18, 0xfffff0bf, v2
	v_xor_b32_e32 v7, 0xfffff07f, v2
	v_xor_b32_e32 v20, 0xfffff03f, v2
	v_xor_b32_e32 v13, 0xffffefff, v2
	v_xor_b32_e32 v22, 0xffffefbf, v2
	v_xor_b32_e32 v15, 0xffffef7f, v2
	v_xor_b32_e32 v24, 0xffffef3f, v2
	v_xor_b32_e32 v17, 0xffffeeff, v2
	v_xor_b32_e32 v26, 0xffffeebf, v2
	v_xor_b32_e32 v19, 0xffffee7f, v2
	v_xor_b32_e32 v28, 0xffffee3f, v2
	v_xor_b32_e32 v21, 0xffffedff, v2
	v_xor_b32_e32 v30, 0xffffedbf, v2
	v_xor_b32_e32 v23, 0xffffed7f, v2
	v_xor_b32_e32 v32, 0xffffed3f, v2
	v_xor_b32_e32 v25, 0xffffecff, v2
	v_xor_b32_e32 v34, 0xffffecbf, v2
	v_xor_b32_e32 v27, 0xffffec7f, v2
	v_xor_b32_e32 v36, 0xffffec3f, v2
	v_xor_b32_e32 v29, 0xffffebff, v2
	v_xor_b32_e32 v38, 0xffffebbf, v2
	v_xor_b32_e32 v31, 0xffffeb7f, v2
	v_xor_b32_e32 v40, 0xffffeb3f, v2
	v_xor_b32_e32 v33, 0xffffeaff, v2
	v_xor_b32_e32 v42, 0xffffeabf, v2
	v_xor_b32_e32 v35, 0xffffea7f, v2
	v_xor_b32_e32 v44, 0xffffea3f, v2
	v_xor_b32_e32 v37, 0xffffe9ff, v2
	v_xor_b32_e32 v46, 0xffffe9bf, v2
	v_xor_b32_e32 v39, 0xffffe97f, v2
	v_xor_b32_e32 v48, 0xffffe93f, v2
	v_xor_b32_e32 v41, 0xffffe8ff, v2
	v_xor_b32_e32 v50, 0xffffe8bf, v2
	v_xor_b32_e32 v43, 0xffffe87f, v2
	v_xor_b32_e32 v52, 0xffffe83f, v2
	v_xor_b32_e32 v45, 0xffffe7ff, v2
	v_xor_b32_e32 v54, 0xffffe7bf, v2
	v_xor_b32_e32 v47, 0xffffe77f, v2
	v_xor_b32_e32 v56, 0xffffe73f, v2
	v_xor_b32_e32 v49, 0xffffe6ff, v2
	v_xor_b32_e32 v58, 0xffffe6bf, v2
	v_xor_b32_e32 v51, 0xffffe67f, v2
	v_xor_b32_e32 v60, 0xffffe63f, v2
	v_xor_b32_e32 v53, 0xffffe5ff, v2
	v_xor_b32_e32 v62, 0xffffe5bf, v2
	v_xor_b32_e32 v55, 0xffffe57f, v2
	v_xor_b32_e32 v64, 0xffffe53f, v2
	v_xor_b32_e32 v57, 0xffffe4ff, v2
	v_xor_b32_e32 v66, 0xffffe4bf, v2
	v_xor_b32_e32 v59, 0xffffe47f, v2
	v_xor_b32_e32 v68, 0xffffe43f, v2
	v_xor_b32_e32 v61, 0xffffe3ff, v2
	v_xor_b32_e32 v70, 0xffffe3bf, v2
	v_xor_b32_e32 v63, 0xffffe37f, v2
	v_xor_b32_e32 v72, 0xffffe33f, v2
	v_xor_b32_e32 v65, 0xffffe2ff, v2
	v_xor_b32_e32 v74, 0xffffe2bf, v2
	v_xor_b32_e32 v67, 0xffffe27f, v2
	v_xor_b32_e32 v76, 0xffffe23f, v2
	v_xor_b32_e32 v69, 0xffffe1ff, v2
	v_xor_b32_e32 v78, 0xffffe1bf, v2
	v_xor_b32_e32 v71, 0xffffe17f, v2
	v_xor_b32_e32 v80, 0xffffe13f, v2
	v_xor_b32_e32 v73, 0xffffe0ff, v2
	v_xor_b32_e32 v82, 0xffffe0bf, v2
	v_xor_b32_e32 v75, 0xffffe07f, v2
	v_xor_b32_e32 v84, 0xffffe03f, v2
	v_lshlrev_b32_e32 v86, 3, v2
	s_branch .LBB0_673

.LBB0_749:
	s_or_b64 exec, exec, s[0:1]
	s_mov_b64 s[2:3], s[58:59]
	s_waitcnt lgkmcnt(0)
	s_barrier
	.p2align 8
	s_load_dwordx2 s[0:1], s[2:3], 0x10
	s_nop 0
	s_load_dwordx2 s[2:3], s[2:3], 0xe0
	v_mov_b32_e32 v1, v208
	v_mov_b32_e32 v3, v0
	v_bfe_u32 v4, v1, 5, 1
	s_waitcnt lgkmcnt(0)
	s_add_u32 s16, s2, 0x11dd8800
	s_addc_u32 s17, s3, 0
	s_add_u32 s18, s2, 0x12dd8800
	s_addc_u32 s19, s3, 0
	s_add_u32 s10, s2, 0x160e8800
	s_addc_u32 s11, s3, 0
	s_add_u32 s12, s2, 0x170e8800
	v_lshlrev_b32_e32 v2, 4, v4
	s_addc_u32 s13, s3, 0
	v_ashrrev_i32_e32 v5, 1, v1
	v_lshl_add_u64 v[2:3], s[2:3], 0, v[2:3]
	s_mov_b64 s[4:5], 0xddd8800
	s_add_u32 s14, s2, 0x160e8808
	s_movk_i32 s2, 0xffe0
	v_and_b32_e32 v197, 31, v1
	v_lshl_add_u64 v[176:177], v[2:3], 0, s[4:5]
	v_lshlrev_b32_e32 v2, 2, v4
	v_bfi_b32 v1, s2, v5, v1
	v_and_b32_e32 v199, 0xffffffe0, v5
	s_addc_u32 s15, s3, 0
	v_add_u32_e32 v204, 0x1f80, v1
	s_mov_b32 s20, 0
	v_lshlrev_b32_e32 v178, 1, v2
	s_mov_b32 s6, s92
	s_branch .LBB0_752

.LBB0_868:
	s_or_b64 exec, exec, s[0:1]
	s_waitcnt lgkmcnt(0)
	s_barrier
	.p2align 8
	s_mov_b64 s[2:3], 0

.LBB0_1059:
	s_or_b64 exec, exec, s[0:1]
	s_mov_b64 s[0:1], s[58:59]
	s_waitcnt lgkmcnt(0)
	s_barrier
	.p2align 8
	s_load_dwordx4 s[16:19], s[0:1], 0x90
	s_nop 0
	s_load_dwordx2 s[0:1], s[0:1], 0xe0
	v_readlane_b32 s2, v254, 52
	v_mov_b32_e32 v137, v208
	v_mov_b32_e32 v1, v208
	v_readlane_b32 s3, v254, 53
	s_andn2_b64 vcc, exec, s[2:3]
	s_waitcnt vmcnt(5)
	v_ashrrev_i32_e32 v156, 6, v1
	s_movk_i32 s2, 0x4080
	v_and_b32_e32 v157, 63, v137
	v_mul_lo_u32 v1, v156, s2
	v_lshlrev_b32_e32 v132, 5, v156
	s_waitcnt vmcnt(4)
	v_lshl_add_u32 v160, v157, 3, v1
	s_cbranch_vccnz .LBB0_1102
	s_waitcnt lgkmcnt(0)
	s_add_u32 s24, s0, 0x11dd8800
	s_addc_u32 s34, s1, 0
	v_ashrrev_i32_e32 v133, 31, v132
	s_add_u32 s38, s0, 0x1580000
	v_lshlrev_b64 v[4:5], 9, v[132:133]
	s_addc_u32 s39, s1, 0
	v_lshl_or_b32 v4, v157, 2, v4
	s_add_u32 s40, s0, 0x9ad8000
	v_lshlrev_b32_e32 v2, 1, v157
	v_lshl_add_u64 v[4:5], s[0:1], 0, v[4:5]
	s_mov_b64 s[2:3], 0x12de8800
	v_readlane_b32 s14, v255, 4
	s_addc_u32 s41, s1, 0
	v_lshl_add_u64 v[134:135], v[4:5], 0, s[2:3]
	v_lshlrev_b32_e32 v133, 2, v2
	v_readlane_b32 s15, v255, 5
	v_readlane_b32 s42, v255, 2
	s_mov_b32 s43, s92

.LBB0_1261:
	s_or_b64 exec, exec, s[0:1]
	v_readlane_b32 s0, v254, 54
	v_readlane_b32 s1, v254, 55
	s_mov_b64 s[2:3], s[58:59]
	v_mov_b32_e32 v1, v208
	s_waitcnt lgkmcnt(0)
	v_mov_b32_e32 v2, v208
	s_andn2_b64 vcc, exec, s[0:1]
	s_barrier
	.p2align 8
	s_cbranch_vccnz .LBB0_1315
	v_ashrrev_i32_e32 v2, 1, v2
	s_load_dwordx2 s[4:5], s[2:3], 0xe0
	s_load_dwordx2 s[0:1], s[2:3], 0x40
	s_nop 0
	s_load_dwordx2 s[2:3], s[2:3], 0x68
	v_and_b32_e32 v132, 0xffffffe0, v2
	v_lshlrev_b32_e32 v3, 3, v1
	v_lshrrev_b32_e32 v2, 5, v2
	s_movk_i32 s6, 0x4080
	v_and_b32_e32 v134, 0x1f8, v3
	v_mul_lo_u32 v2, v2, s6
	v_add_u32_e32 v3, v134, v2
	s_waitcnt lgkmcnt(0)
	s_add_u32 s24, s4, 0x12de8800
	v_add_u32_e32 v5, 0x3e7c, v3
	s_addc_u32 s28, s5, 0
	v_or_b32_e32 v4, 4, v3
	v_mov_b32_e32 v135, v0
	v_cmp_ge_u32_e32 vcc, v5, v3
	v_add_u32_e32 v3, 0x3e80, v3
	s_add_u32 s29, s4, 0x1980000
	v_lshl_add_u64 v[136:137], s[2:3], 0, v[134:135]
	v_cmp_ge_u32_e64 s[2:3], v3, v4
	s_addc_u32 s30, s5, 0
	s_and_b64 s[10:11], vcc, s[2:3]
	s_add_u32 s12, s4, 0x13068800
	s_addc_u32 s13, s5, 0
	v_and_b32_e32 v1, 63, v1
	s_add_u32 s31, s4, 0x12fe8800
	v_mov_b32_e32 v133, v132
	v_lshl_add_u32 v135, v1, 3, v2
	s_addc_u32 s34, s5, 0
	v_readlane_b32 s38, v255, 0
	s_mov_b32 s39, s92
	s_branch .LBB0_1264

.LBB0_1367:
	s_or_b64 exec, exec, s[0:1]
	s_mov_b64 s[2:3], s[58:59]
	s_waitcnt lgkmcnt(0)
	s_barrier
	.p2align 8
	s_load_dwordx2 s[0:1], s[2:3], 0x10
	s_load_dwordx2 s[76:77], s[2:3], 0xe0
	s_waitcnt vmcnt(0)
	v_mov_b32_e32 v144, v208
	s_movk_i32 s20, 0x1020
	v_add_u32_e32 v9, 0x200, v144
	s_waitcnt lgkmcnt(0)
	s_add_u32 s18, s76, 0xddd8800
	v_ashrrev_i32_e32 v10, 4, v9
	v_add_u32_e32 v9, 0x300, v144
	s_addc_u32 s19, s77, 0
	v_ashrrev_i32_e32 v12, 4, v9
	v_max_i32_e32 v9, 0x104, v144
	s_add_u32 s86, s76, 0x14968800
	v_sub_u32_e32 v9, v9, v144
	s_addc_u32 s87, s77, 0
	v_add_u32_e32 v9, 0xff, v9
	v_ashrrev_i32_e32 v176, 6, v144
	s_add_u32 s16, s76, 0x1cae8800
	v_lshrrev_b32_e32 v11, 8, v9
	v_cmp_gt_i32_e64 s[4:5], s20, v144
	s_addc_u32 s17, s77, 0
	v_mul_lo_u32 v184, v176, s20
	v_add_u32_e32 v11, 1, v11
	v_cmp_lt_u32_e64 s[20:21], s53, v9
	s_add_u32 s43, s76, 0x20ae8800
	v_and_b32_e32 v193, 0x1fffffe, v11
	v_writelane_b32 v255, s20, 28
	s_addc_u32 s44, s77, 0
	v_and_b32_e32 v177, 31, v144
	v_writelane_b32 v255, s21, 29
	v_cmp_ne_u32_e64 s[20:21], v11, v193
	v_bfe_u32 v1, v144, 5, 1
	v_add_u32_e32 v145, 0x100, v144
	v_writelane_b32 v255, s20, 30
	s_add_u32 s94, s76, 0x13068800
	v_lshlrev_b32_e32 v4, 2, v1
	v_mul_u32_u24_e32 v7, 0x204, v177
	v_ashrrev_i32_e32 v6, 4, v144
	v_ashrrev_i32_e32 v8, 4, v145
	v_writelane_b32 v255, s21, 31
	v_lshlrev_b32_e32 v9, 2, v144
	s_addc_u32 s95, s77, 0
	s_mov_b32 s20, 0xb400
	v_and_b32_e32 v146, 63, v144
	v_lshlrev_b32_e32 v2, 3, v1
	v_lshlrev_b32_e32 v3, 4, v144
	v_lshlrev_b32_e32 v14, 4, v1
	v_lshlrev_b32_e32 v180, 3, v176
	s_movk_i32 s8, 0x110
	v_lshlrev_b32_e32 v1, 6, v1
	v_add_u32_e32 v195, 0xfc80, v9
	v_add_u32_e32 v196, 0xb400, v9
	v_add3_u32 v199, v7, v4, s20
	s_add_u32 s20, s76, 0x12fe8800
	v_ashrrev_i32_e32 v13, 31, v12
	v_ashrrev_i32_e32 v11, 31, v10
	v_ashrrev_i32_e32 v9, 31, v8
	v_ashrrev_i32_e32 v7, 31, v6
	v_lshlrev_b32_e32 v178, 2, v146
	v_and_b32_e32 v3, 0xf0, v3
	v_mul_u32_u24_e32 v5, 0x110, v177
	v_or_b32_e32 v148, 64, v146
	v_lshlrev_b32_e32 v15, 9, v176
	v_mul_lo_u32 v16, v6, s8
	v_mul_lo_u32 v17, v8, s8
	v_mul_lo_u32 v18, v10, s8
	v_mul_lo_u32 v19, v12, s8
	v_or_b32_e32 v185, 1, v180
	v_sub_u32_e32 v198, v177, v1
	v_and_b32_e32 v1, 15, v144
	s_addc_u32 s21, s77, 0
	v_lshlrev_b64 v[12:13], 8, v[12:13]
	v_lshlrev_b64 v[10:11], 8, v[10:11]
	v_lshlrev_b64 v[8:9], 8, v[8:9]
	v_lshlrev_b64 v[6:7], 8, v[6:7]
	v_cmp_gt_i32_e64 s[2:3], s56, v144
	v_mul_lo_u32 v179, v176, s56
	s_mov_b32 s42, 0
	v_cmp_eq_u32_e64 s[6:7], 0, v146
	v_or_b32_e32 v181, v178, v15
	v_lshlrev_b32_e32 v182, 6, v146
	v_lshlrev_b32_e32 v183, 6, v148
	s_movk_i32 s97, 0x110
	v_cmp_gt_u32_e64 s[8:9], 64, v144
	v_cmp_eq_u32_e64 s[10:11], 1, v176
	v_cmp_eq_u32_e64 s[12:13], 2, v176
	v_cmp_eq_u32_e64 s[14:15], 3, v176
	v_mul_lo_u32 v186, v185, s56
	v_or_b32_e32 v187, 2, v180
	v_or_b32_e32 v188, 3, v180
	v_or_b32_e32 v189, 4, v180
	v_or_b32_e32 v190, 5, v180
	v_or_b32_e32 v191, 6, v180
	v_or_b32_e32 v192, 7, v180
	v_lshl_add_u32 v194, v193, 8, v144
	v_mov_b32_e32 v147, v146
	v_mov_b32_e32 v149, v148
	v_add_u32_e32 v197, 0xffffff00, v144
	v_lshlrev_b32_e32 v150, 4, v1
	v_mov_b32_e32 v151, v0
	v_lshl_add_u64 v[152:153], s[20:21], 0, v[12:13]
	v_lshl_add_u64 v[154:155], s[20:21], 0, v[10:11]
	v_lshl_add_u64 v[156:157], s[20:21], 0, v[8:9]
	v_lshl_add_u64 v[158:159], s[20:21], 0, v[6:7]
	v_add_u32_e32 v200, 0xf480, v15
	v_lshlrev_b32_e32 v160, 1, v2
	v_lshlrev_b32_e32 v162, 2, v4
	v_add_u32_e32 v201, v3, v16
	v_add_u32_e32 v202, v3, v17
	v_add_u32_e32 v203, v3, v18
	v_add_u32_e32 v204, v3, v19
	v_add_u32_e32 v205, v5, v14
	s_mov_b32 s34, s92
	s_branch .LBB0_1370

.LBB0_1508:
	s_waitcnt lgkmcnt(0)
	v_fmac_f32_e32 v73, 0x3e0293ee, v17
	v_cmp_lt_i32_e32 vcc, s62, v42
	s_movk_i32 s20, 0x39f
	v_fmac_f32_e32 v72, 0x3e0293ee, v32
	v_cndmask_b32_e32 v17, v221, v73, vcc
	v_cmp_lt_i32_e32 vcc, s20, v42
	v_fmac_f32_e32 v71, 0x3e0293ee, v16
	s_movk_i32 s20, 0x38f
	v_cndmask_b32_e32 v32, v221, v72, vcc
	v_cmp_lt_i32_e32 vcc, s81, v42
	v_fmac_f32_e32 v70, 0x3e0293ee, v31
	v_fmac_f32_e32 v69, 0x3e0293ee, v15
	v_cndmask_b32_e32 v16, v221, v71, vcc
	v_sub_f32_e32 v16, v16, v1
	v_cmp_lt_i32_e32 vcc, s20, v42
	v_exp_f32_e32 v71, v16
	s_movk_i32 s20, 0x37f
	v_cndmask_b32_e32 v16, v221, v70, vcc
	v_cmp_lt_i32_e32 vcc, s80, v42
	v_fmac_f32_e32 v68, 0x3e0293ee, v30
	v_fmac_f32_e32 v67, 0x3e0293ee, v14
	v_cndmask_b32_e32 v15, v221, v69, vcc
	v_cmp_lt_i32_e32 vcc, s20, v42
	s_movk_i32 s20, 0x17f
	v_fmac_f32_e32 v66, 0x3e0293ee, v29
	v_cndmask_b32_e32 v30, v221, v68, vcc
	v_cmp_lt_i32_e32 vcc, s20, v42
	s_movk_i32 s20, 0x32f
	v_sub_f32_e32 v17, v17, v1
	v_cndmask_b32_e32 v14, v221, v67, vcc
	v_cmp_lt_i32_e32 vcc, s20, v42
	v_sub_f32_e32 v16, v16, v1
	v_sub_f32_e32 v14, v14, v1
	v_cndmask_b32_e32 v29, v221, v66, vcc
	v_sub_f32_e32 v29, v29, v1
	v_fmac_f32_e32 v65, 0x3e0293ee, v13
	v_cmp_lt_i32_e32 vcc, s63, v42
	s_movk_i32 s20, 0x31f
	v_exp_f32_e32 v17, v17
	v_exp_f32_e32 v31, v16
	v_exp_f32_e32 v14, v14
	v_exp_f32_e32 v29, v29
	v_cndmask_b32_e32 v13, v221, v65, vcc
	v_fmac_f32_e32 v64, 0x3e0293ee, v28
	v_cmp_lt_i32_e32 vcc, s20, v42
	v_fmac_f32_e32 v63, 0x3e0293ee, v12
	s_movk_i32 s20, 0x30f
	v_cndmask_b32_e32 v28, v221, v64, vcc
	v_cmp_lt_i32_e32 vcc, s54, v42
	v_fmac_f32_e32 v62, 0x3e0293ee, v27
	v_mul_f32_e32 v16, v82, v17
	v_cndmask_b32_e32 v12, v221, v63, vcc
	v_sub_f32_e32 v12, v12, v1
	v_cmp_lt_i32_e32 vcc, s20, v42
	v_mul_f32_e32 v17, v82, v31
	v_mul_f32_e32 v31, v82, v14
	v_mul_f32_e32 v14, v82, v29
	v_exp_f32_e32 v29, v12
	v_cndmask_b32_e32 v12, v221, v62, vcc
	v_fmac_f32_e32 v61, 0x3e0293ee, v11
	v_cmp_lt_i32_e32 vcc, s73, v42
	s_movk_i32 s20, 0x2ff
	v_fmac_f32_e32 v60, 0x3e0293ee, v26
	v_cndmask_b32_e32 v11, v221, v61, vcc
	v_cmp_lt_i32_e32 vcc, s20, v42
	v_fmac_f32_e32 v59, 0x3e0293ee, v10
	s_movk_i32 s20, 0x2af
	v_cndmask_b32_e32 v26, v221, v60, vcc
	v_cmp_lt_i32_e32 vcc, s53, v42
	v_fmac_f32_e32 v58, 0x3e0293ee, v25
	v_sub_f32_e32 v13, v13, v1
	v_cndmask_b32_e32 v10, v221, v59, vcc
	v_cmp_lt_i32_e32 vcc, s20, v42
	v_sub_f32_e32 v10, v10, v1
	v_fmac_f32_e32 v57, 0x3e0293ee, v9
	v_cndmask_b32_e32 v25, v221, v58, vcc
	v_sub_f32_e32 v25, v25, v1
	v_cmp_lt_i32_e32 vcc, s72, v42
	s_movk_i32 s20, 0x29f
	v_exp_f32_e32 v13, v13
	v_exp_f32_e32 v10, v10
	v_exp_f32_e32 v25, v25
	v_cndmask_b32_e32 v9, v221, v57, vcc
	v_fmac_f32_e32 v56, 0x3e0293ee, v24
	v_cmp_lt_i32_e32 vcc, s20, v42
	v_fmac_f32_e32 v55, 0x3e0293ee, v8
	s_movk_i32 s20, 0x28f
	v_cndmask_b32_e32 v24, v221, v56, vcc
	v_cmp_lt_i32_e32 vcc, s71, v42
	v_sub_f32_e32 v12, v12, v1
	v_fmac_f32_e32 v54, 0x3e0293ee, v23
	v_cndmask_b32_e32 v8, v221, v55, vcc
	v_sub_f32_e32 v8, v8, v1
	v_cmp_lt_i32_e32 vcc, s20, v42
	s_movk_i32 s20, 0x8f
	v_exp_f32_e32 v27, v12
	v_mul_f32_e32 v12, v82, v13
	v_mul_f32_e32 v13, v82, v29
	v_mul_f32_e32 v29, v82, v10
	v_mul_f32_e32 v10, v82, v25
	v_exp_f32_e32 v25, v8
	v_cndmask_b32_e32 v8, v221, v54, vcc
	v_fmac_f32_e32 v53, 0x3e0293ee, v7
	v_cmp_lt_i32_e32 vcc, s20, v42
	s_movk_i32 s20, 0x27f
	v_sub_f32_e32 v9, v9, v1
	v_cndmask_b32_e32 v7, v221, v53, vcc
	v_sub_f32_e32 v7, v7, v1
	v_fmac_f32_e32 v52, 0x3e0293ee, v22
	v_cmp_lt_i32_e32 vcc, s20, v42
	v_exp_f32_e32 v9, v9
	v_exp_f32_e32 v7, v7
	v_cndmask_b32_e32 v22, v221, v52, vcc
	v_fmac_f32_e32 v51, 0x3e0293ee, v6
	v_cmp_lt_i32_e32 vcc, s69, v42
	s_movk_i32 s20, 0x22f
	v_fmac_f32_e32 v50, 0x3e0293ee, v21
	v_cndmask_b32_e32 v6, v221, v51, vcc
	v_cmp_lt_i32_e32 vcc, s20, v42
	v_fmac_f32_e32 v49, 0x3e0293ee, v5
	s_movk_i32 s20, 0x21f
	v_cndmask_b32_e32 v21, v221, v50, vcc
	v_cmp_lt_i32_e32 vcc, 47, v42
	v_sub_f32_e32 v8, v8, v1
	v_fmac_f32_e32 v48, 0x3e0293ee, v20
	v_cndmask_b32_e32 v5, v221, v49, vcc
	v_cmp_lt_i32_e32 vcc, s20, v42
	v_exp_f32_e32 v23, v8
	v_mul_f32_e32 v8, v82, v9
	v_mul_f32_e32 v9, v82, v25
	v_mul_f32_e32 v25, v82, v7
	v_cndmask_b32_e32 v7, v221, v48, vcc
	v_fmac_f32_e32 v47, 0x3e0293ee, v4
	v_cmp_lt_i32_e32 vcc, 31, v42
	s_movk_i32 s20, 0x20f
	v_sub_f32_e32 v5, v5, v1
	v_sub_f32_e32 v7, v7, v1
	v_cndmask_b32_e32 v4, v221, v47, vcc
	v_fmac_f32_e32 v46, 0x3e0293ee, v19
	v_cmp_lt_i32_e32 vcc, s20, v42
	v_exp_f32_e32 v5, v5
	v_exp_f32_e32 v20, v7
	v_cndmask_b32_e32 v7, v221, v46, vcc
	v_fmac_f32_e32 v45, 0x3e0293ee, v3
	v_cmp_lt_i32_e32 vcc, 15, v42
	v_fmac_f32_e32 v44, 0x3e0293ee, v18
	v_fmac_f32_e32 v43, 0x3e0293ee, v2
	v_cndmask_b32_e32 v3, v221, v45, vcc
	v_cmp_lt_i32_e32 vcc, s65, v42
	s_movk_i32 s20, 0x3af
	v_sub_f32_e32 v7, v7, v1
	v_cndmask_b32_e32 v18, v221, v44, vcc
	v_cmp_lt_i32_e32 vcc, -1, v42
	v_fmac_f32_e32 v41, 0x3e0293ee, v33
	v_sub_f32_e32 v15, v15, v1
	v_cndmask_b32_e32 v2, v221, v43, vcc
	v_cmp_lt_i32_e32 vcc, s20, v42
	v_sub_f32_e32 v30, v30, v1
	v_sub_f32_e32 v11, v11, v1
	v_sub_f32_e32 v26, v26, v1
	v_sub_f32_e32 v22, v22, v1
	v_sub_f32_e32 v6, v6, v1
	v_sub_f32_e32 v21, v21, v1
	v_exp_f32_e32 v19, v7
	v_mul_f32_e32 v7, v82, v5
	v_mul_f32_e32 v5, v82, v20
	v_sub_f32_e32 v3, v3, v1
	v_sub_f32_e32 v18, v18, v1
	v_sub_f32_e32 v2, v2, v1
	v_cndmask_b32_e32 v20, v221, v41, vcc
	v_sub_f32_e32 v32, v32, v1
	v_exp_f32_e32 v15, v15
	v_exp_f32_e32 v30, v30
	v_sub_f32_e32 v28, v28, v1
	v_exp_f32_e32 v11, v11
	v_exp_f32_e32 v26, v26
	v_sub_f32_e32 v24, v24, v1
	v_exp_f32_e32 v22, v22
	v_exp_f32_e32 v6, v6
	v_exp_f32_e32 v21, v21
	v_sub_f32_e32 v4, v4, v1
	v_exp_f32_e32 v3, v3
	v_exp_f32_e32 v18, v18
	v_exp_f32_e32 v2, v2
	v_sub_f32_e32 v20, v20, v1
	v_exp_f32_e32 v32, v32
	v_exp_f32_e32 v28, v28
	v_exp_f32_e32 v24, v24
	v_exp_f32_e32 v4, v4
	v_exp_f32_e32 v20, v20
	v_mul_f32_e32 v15, v82, v15
	v_mul_f32_e32 v30, v82, v30
	v_mul_f32_e32 v27, v82, v27
	v_mul_f32_e32 v11, v82, v11
	v_mul_f32_e32 v26, v82, v26
	v_mul_f32_e32 v23, v82, v23
	v_mul_f32_e32 v22, v82, v22
	v_mul_f32_e32 v50, v82, v6
	v_mul_f32_e32 v6, v82, v21
	v_mul_f32_e32 v19, v82, v19
	v_mul_f32_e32 v3, v82, v3
	v_mul_f32_e32 v18, v82, v18
	v_mul_f32_e32 v21, v82, v2
	v_mul_f32_e32 v32, v82, v32
	v_mul_f32_e32 v70, v82, v71
	v_mul_f32_e32 v28, v82, v28
	v_mul_f32_e32 v24, v82, v24
	v_mul_f32_e32 v4, v82, v4
	v_mul_f32_e32 v2, v82, v20
	v_add_f32_e32 v3, v21, v3
	v_add_f32_e32 v20, v50, v25
	v_add_f32_e32 v11, v29, v11
	v_add_f32_e32 v21, v31, v15
	v_add_f32_e32 v18, v18, v19
	v_add_f32_e32 v19, v22, v23
	v_add_f32_e32 v22, v26, v27
	v_add_f32_e32 v23, v30, v17
	v_add_f32_e32 v17, v3, v4
	v_add_f32_e32 v15, v20, v9
	v_add_f32_e32 v13, v11, v13
	v_add_f32_e32 v11, v21, v70
	v_add_f32_e32 v9, v18, v5
	v_add_f32_e32 v5, v19, v24
	v_add_f32_e32 v4, v22, v28
	v_add_f32_e32 v3, v23, v32
	s_and_saveexec_b64 s[20:21], s[8:9]
	s_cbranch_execz .LBB0_1510
	v_fma_f32 v17, 0.5, v7, v17
	v_fma_f32 v15, 0.5, v8, v15
	v_fma_f32 v13, 0.5, v12, v13
	v_fma_f32 v11, 0.5, v16, v11
	v_fma_f32 v9, 0.5, v6, v9
	v_fma_f32 v5, 0.5, v10, v5
	v_fma_f32 v4, 0.5, v14, v4
	v_fma_f32 v3, 0.5, v2, v3
	s_mov_b64 vcc, exec
	s_mov_b32 exec_lo, 0
	ds_read2_b32 v[18:19], v40 offset0:0 offset1:1
	ds_read2_b32 v[20:21], v40 offset0:2 offset1:3
	ds_read2_b32 v[22:23], v40 offset0:4 offset1:5
	ds_read2_b32 v[24:25], v40 offset0:6 offset1:7
	ds_read2_b32 v[26:27], v40 offset0:8 offset1:9
	ds_read2_b32 v[28:29], v40 offset0:10 offset1:11
	ds_read2_b32 v[30:31], v40 offset0:12 offset1:13
	ds_read2_b32 v[32:33], v40 offset0:14 offset1:15
	s_waitcnt lgkmcnt(0)
	v_add_f32_e32 v18, v17, v18
	v_fmac_f32_e32 v19, 0.5, v7
	v_add_f32_e32 v20, v15, v20
	v_fmac_f32_e32 v21, 0.5, v8
	v_add_f32_e32 v22, v13, v22
	v_fmac_f32_e32 v23, 0.5, v12
	v_add_f32_e32 v24, v11, v24
	v_fmac_f32_e32 v25, 0.5, v16
	v_add_f32_e32 v26, v9, v26
	v_fmac_f32_e32 v27, 0.5, v6
	v_add_f32_e32 v28, v5, v28
	v_fmac_f32_e32 v29, 0.5, v10
	v_add_f32_e32 v30, v4, v30
	v_fmac_f32_e32 v31, 0.5, v14
	v_add_f32_e32 v32, v3, v32
	v_fmac_f32_e32 v33, 0.5, v2
	ds_write2_b32 v40, v18, v19 offset0:0 offset1:1
	ds_write2_b32 v40, v20, v21 offset0:2 offset1:3
	ds_write2_b32 v40, v22, v23 offset0:4 offset1:5
	ds_write2_b32 v40, v24, v25 offset0:6 offset1:7
	ds_write2_b32 v40, v26, v27 offset0:8 offset1:9
	ds_write2_b32 v40, v28, v29 offset0:10 offset1:11
	ds_write2_b32 v40, v30, v31 offset0:12 offset1:13
	ds_write2_b32 v40, v32, v33 offset0:14 offset1:15
	s_waitcnt lgkmcnt(0)
	s_mov_b32 exec_lo, vcc_lo
	s_mov_b32 exec_hi, 0
	ds_read2_b32 v[18:19], v40 offset0:0 offset1:1
	ds_read2_b32 v[20:21], v40 offset0:2 offset1:3
	ds_read2_b32 v[22:23], v40 offset0:4 offset1:5
	ds_read2_b32 v[24:25], v40 offset0:6 offset1:7
	ds_read2_b32 v[26:27], v40 offset0:8 offset1:9
	ds_read2_b32 v[28:29], v40 offset0:10 offset1:11
	ds_read2_b32 v[30:31], v40 offset0:12 offset1:13
	ds_read2_b32 v[32:33], v40 offset0:14 offset1:15
	s_waitcnt lgkmcnt(0)
	v_add_f32_e32 v18, v17, v18
	v_fmac_f32_e32 v19, 0.5, v7
	v_add_f32_e32 v20, v15, v20
	v_fmac_f32_e32 v21, 0.5, v8
	v_add_f32_e32 v22, v13, v22
	v_fmac_f32_e32 v23, 0.5, v12
	v_add_f32_e32 v24, v11, v24
	v_fmac_f32_e32 v25, 0.5, v16
	v_add_f32_e32 v26, v9, v26
	v_fmac_f32_e32 v27, 0.5, v6
	v_add_f32_e32 v28, v5, v28
	v_fmac_f32_e32 v29, 0.5, v10
	v_add_f32_e32 v30, v4, v30
	v_fmac_f32_e32 v31, 0.5, v14
	v_add_f32_e32 v32, v3, v32
	v_fmac_f32_e32 v33, 0.5, v2
	ds_write2_b32 v40, v18, v19 offset0:0 offset1:1
	ds_write2_b32 v40, v20, v21 offset0:2 offset1:3
	ds_write2_b32 v40, v22, v23 offset0:4 offset1:5
	ds_write2_b32 v40, v24, v25 offset0:6 offset1:7
	ds_write2_b32 v40, v26, v27 offset0:8 offset1:9
	ds_write2_b32 v40, v28, v29 offset0:10 offset1:11
	ds_write2_b32 v40, v30, v31 offset0:12 offset1:13
	ds_write2_b32 v40, v32, v33 offset0:14 offset1:15
	s_waitcnt lgkmcnt(0)
	s_mov_b64 exec, vcc
.LBB0_1510:
	s_or_b64 exec, exec, s[20:21]
	s_barrier
	s_and_saveexec_b64 s[20:21], s[10:11]
	s_cbranch_execz .LBB0_1512
	v_fma_f32 v17, 0.5, v7, v17
	v_fma_f32 v15, 0.5, v8, v15
	v_fma_f32 v13, 0.5, v12, v13
	v_fma_f32 v11, 0.5, v16, v11
	v_fma_f32 v9, 0.5, v6, v9
	v_fma_f32 v5, 0.5, v10, v5
	v_fma_f32 v4, 0.5, v14, v4
	v_fma_f32 v3, 0.5, v2, v3
	s_mov_b64 vcc, exec
	s_mov_b32 exec_lo, 0
	ds_read2_b32 v[18:19], v40 offset0:0 offset1:1
	ds_read2_b32 v[20:21], v40 offset0:2 offset1:3
	ds_read2_b32 v[22:23], v40 offset0:4 offset1:5
	ds_read2_b32 v[24:25], v40 offset0:6 offset1:7
	ds_read2_b32 v[26:27], v40 offset0:8 offset1:9
	ds_read2_b32 v[28:29], v40 offset0:10 offset1:11
	ds_read2_b32 v[30:31], v40 offset0:12 offset1:13
	ds_read2_b32 v[32:33], v40 offset0:14 offset1:15
	s_waitcnt lgkmcnt(0)
	v_add_f32_e32 v18, v17, v18
	v_fmac_f32_e32 v19, 0.5, v7
	v_add_f32_e32 v20, v15, v20
	v_fmac_f32_e32 v21, 0.5, v8
	v_add_f32_e32 v22, v13, v22
	v_fmac_f32_e32 v23, 0.5, v12
	v_add_f32_e32 v24, v11, v24
	v_fmac_f32_e32 v25, 0.5, v16
	v_add_f32_e32 v26, v9, v26
	v_fmac_f32_e32 v27, 0.5, v6
	v_add_f32_e32 v28, v5, v28
	v_fmac_f32_e32 v29, 0.5, v10
	v_add_f32_e32 v30, v4, v30
	v_fmac_f32_e32 v31, 0.5, v14
	v_add_f32_e32 v32, v3, v32
	v_fmac_f32_e32 v33, 0.5, v2
	ds_write2_b32 v40, v18, v19 offset0:0 offset1:1
	ds_write2_b32 v40, v20, v21 offset0:2 offset1:3
	ds_write2_b32 v40, v22, v23 offset0:4 offset1:5
	ds_write2_b32 v40, v24, v25 offset0:6 offset1:7
	ds_write2_b32 v40, v26, v27 offset0:8 offset1:9
	ds_write2_b32 v40, v28, v29 offset0:10 offset1:11
	ds_write2_b32 v40, v30, v31 offset0:12 offset1:13
	ds_write2_b32 v40, v32, v33 offset0:14 offset1:15
	s_waitcnt lgkmcnt(0)
	s_mov_b32 exec_lo, vcc_lo
	s_mov_b32 exec_hi, 0
	ds_read2_b32 v[18:19], v40 offset0:0 offset1:1
	ds_read2_b32 v[20:21], v40 offset0:2 offset1:3
	ds_read2_b32 v[22:23], v40 offset0:4 offset1:5
	ds_read2_b32 v[24:25], v40 offset0:6 offset1:7
	ds_read2_b32 v[26:27], v40 offset0:8 offset1:9
	ds_read2_b32 v[28:29], v40 offset0:10 offset1:11
	ds_read2_b32 v[30:31], v40 offset0:12 offset1:13
	ds_read2_b32 v[32:33], v40 offset0:14 offset1:15
	s_waitcnt lgkmcnt(0)
	v_add_f32_e32 v18, v17, v18
	v_fmac_f32_e32 v19, 0.5, v7
	v_add_f32_e32 v20, v15, v20
	v_fmac_f32_e32 v21, 0.5, v8
	v_add_f32_e32 v22, v13, v22
	v_fmac_f32_e32 v23, 0.5, v12
	v_add_f32_e32 v24, v11, v24
	v_fmac_f32_e32 v25, 0.5, v16
	v_add_f32_e32 v26, v9, v26
	v_fmac_f32_e32 v27, 0.5, v6
	v_add_f32_e32 v28, v5, v28
	v_fmac_f32_e32 v29, 0.5, v10
	v_add_f32_e32 v30, v4, v30
	v_fmac_f32_e32 v31, 0.5, v14
	v_add_f32_e32 v32, v3, v32
	v_fmac_f32_e32 v33, 0.5, v2
	ds_write2_b32 v40, v18, v19 offset0:0 offset1:1
	ds_write2_b32 v40, v20, v21 offset0:2 offset1:3
	ds_write2_b32 v40, v22, v23 offset0:4 offset1:5
	ds_write2_b32 v40, v24, v25 offset0:6 offset1:7
	ds_write2_b32 v40, v26, v27 offset0:8 offset1:9
	ds_write2_b32 v40, v28, v29 offset0:10 offset1:11
	ds_write2_b32 v40, v30, v31 offset0:12 offset1:13
	ds_write2_b32 v40, v32, v33 offset0:14 offset1:15
	s_waitcnt lgkmcnt(0)
	s_mov_b64 exec, vcc
.LBB0_1512:
	s_or_b64 exec, exec, s[20:21]
	s_barrier
	s_and_saveexec_b64 s[20:21], s[12:13]
	s_cbranch_execz .LBB0_1514
	v_fma_f32 v17, 0.5, v7, v17
	v_fma_f32 v15, 0.5, v8, v15
	v_fma_f32 v13, 0.5, v12, v13
	v_fma_f32 v11, 0.5, v16, v11
	v_fma_f32 v9, 0.5, v6, v9
	v_fma_f32 v5, 0.5, v10, v5
	v_fma_f32 v4, 0.5, v14, v4
	v_fma_f32 v3, 0.5, v2, v3
	s_mov_b64 vcc, exec
	s_mov_b32 exec_lo, 0
	ds_read2_b32 v[18:19], v40 offset0:0 offset1:1
	ds_read2_b32 v[20:21], v40 offset0:2 offset1:3
	ds_read2_b32 v[22:23], v40 offset0:4 offset1:5
	ds_read2_b32 v[24:25], v40 offset0:6 offset1:7
	ds_read2_b32 v[26:27], v40 offset0:8 offset1:9
	ds_read2_b32 v[28:29], v40 offset0:10 offset1:11
	ds_read2_b32 v[30:31], v40 offset0:12 offset1:13
	ds_read2_b32 v[32:33], v40 offset0:14 offset1:15
	s_waitcnt lgkmcnt(0)
	v_add_f32_e32 v18, v17, v18
	v_fmac_f32_e32 v19, 0.5, v7
	v_add_f32_e32 v20, v15, v20
	v_fmac_f32_e32 v21, 0.5, v8
	v_add_f32_e32 v22, v13, v22
	v_fmac_f32_e32 v23, 0.5, v12
	v_add_f32_e32 v24, v11, v24
	v_fmac_f32_e32 v25, 0.5, v16
	v_add_f32_e32 v26, v9, v26
	v_fmac_f32_e32 v27, 0.5, v6
	v_add_f32_e32 v28, v5, v28
	v_fmac_f32_e32 v29, 0.5, v10
	v_add_f32_e32 v30, v4, v30
	v_fmac_f32_e32 v31, 0.5, v14
	v_add_f32_e32 v32, v3, v32
	v_fmac_f32_e32 v33, 0.5, v2
	ds_write2_b32 v40, v18, v19 offset0:0 offset1:1
	ds_write2_b32 v40, v20, v21 offset0:2 offset1:3
	ds_write2_b32 v40, v22, v23 offset0:4 offset1:5
	ds_write2_b32 v40, v24, v25 offset0:6 offset1:7
	ds_write2_b32 v40, v26, v27 offset0:8 offset1:9
	ds_write2_b32 v40, v28, v29 offset0:10 offset1:11
	ds_write2_b32 v40, v30, v31 offset0:12 offset1:13
	ds_write2_b32 v40, v32, v33 offset0:14 offset1:15
	s_waitcnt lgkmcnt(0)
	s_mov_b32 exec_lo, vcc_lo
	s_mov_b32 exec_hi, 0
	ds_read2_b32 v[18:19], v40 offset0:0 offset1:1
	ds_read2_b32 v[20:21], v40 offset0:2 offset1:3
	ds_read2_b32 v[22:23], v40 offset0:4 offset1:5
	ds_read2_b32 v[24:25], v40 offset0:6 offset1:7
	ds_read2_b32 v[26:27], v40 offset0:8 offset1:9
	ds_read2_b32 v[28:29], v40 offset0:10 offset1:11
	ds_read2_b32 v[30:31], v40 offset0:12 offset1:13
	ds_read2_b32 v[32:33], v40 offset0:14 offset1:15
	s_waitcnt lgkmcnt(0)
	v_add_f32_e32 v18, v17, v18
	v_fmac_f32_e32 v19, 0.5, v7
	v_add_f32_e32 v20, v15, v20
	v_fmac_f32_e32 v21, 0.5, v8
	v_add_f32_e32 v22, v13, v22
	v_fmac_f32_e32 v23, 0.5, v12
	v_add_f32_e32 v24, v11, v24
	v_fmac_f32_e32 v25, 0.5, v16
	v_add_f32_e32 v26, v9, v26
	v_fmac_f32_e32 v27, 0.5, v6
	v_add_f32_e32 v28, v5, v28
	v_fmac_f32_e32 v29, 0.5, v10
	v_add_f32_e32 v30, v4, v30
	v_fmac_f32_e32 v31, 0.5, v14
	v_add_f32_e32 v32, v3, v32
	v_fmac_f32_e32 v33, 0.5, v2
	ds_write2_b32 v40, v18, v19 offset0:0 offset1:1
	ds_write2_b32 v40, v20, v21 offset0:2 offset1:3
	ds_write2_b32 v40, v22, v23 offset0:4 offset1:5
	ds_write2_b32 v40, v24, v25 offset0:6 offset1:7
	ds_write2_b32 v40, v26, v27 offset0:8 offset1:9
	ds_write2_b32 v40, v28, v29 offset0:10 offset1:11
	ds_write2_b32 v40, v30, v31 offset0:12 offset1:13
	ds_write2_b32 v40, v32, v33 offset0:14 offset1:15
	s_waitcnt lgkmcnt(0)
	s_mov_b64 exec, vcc
.LBB0_1514:
	s_or_b64 exec, exec, s[20:21]
	s_barrier
	s_and_saveexec_b64 s[20:21], s[14:15]
	s_cbranch_execz .LBB0_1473
	v_fma_f32 v17, 0.5, v7, v17
	v_fma_f32 v15, 0.5, v8, v15
	v_fma_f32 v13, 0.5, v12, v13
	v_fma_f32 v11, 0.5, v16, v11
	v_fma_f32 v9, 0.5, v6, v9
	v_fma_f32 v5, 0.5, v10, v5
	v_fma_f32 v4, 0.5, v14, v4
	v_fma_f32 v3, 0.5, v2, v3
	s_mov_b64 vcc, exec
	s_mov_b32 exec_lo, 0
	ds_read2_b32 v[18:19], v40 offset0:0 offset1:1
	ds_read2_b32 v[20:21], v40 offset0:2 offset1:3
	ds_read2_b32 v[22:23], v40 offset0:4 offset1:5
	ds_read2_b32 v[24:25], v40 offset0:6 offset1:7
	ds_read2_b32 v[26:27], v40 offset0:8 offset1:9
	ds_read2_b32 v[28:29], v40 offset0:10 offset1:11
	ds_read2_b32 v[30:31], v40 offset0:12 offset1:13
	ds_read2_b32 v[32:33], v40 offset0:14 offset1:15
	s_waitcnt lgkmcnt(0)
	v_add_f32_e32 v18, v17, v18
	v_fmac_f32_e32 v19, 0.5, v7
	v_add_f32_e32 v20, v15, v20
	v_fmac_f32_e32 v21, 0.5, v8
	v_add_f32_e32 v22, v13, v22
	v_fmac_f32_e32 v23, 0.5, v12
	v_add_f32_e32 v24, v11, v24
	v_fmac_f32_e32 v25, 0.5, v16
	v_add_f32_e32 v26, v9, v26
	v_fmac_f32_e32 v27, 0.5, v6
	v_add_f32_e32 v28, v5, v28
	v_fmac_f32_e32 v29, 0.5, v10
	v_add_f32_e32 v30, v4, v30
	v_fmac_f32_e32 v31, 0.5, v14
	v_add_f32_e32 v32, v3, v32
	v_fmac_f32_e32 v33, 0.5, v2
	ds_write2_b32 v40, v18, v19 offset0:0 offset1:1
	ds_write2_b32 v40, v20, v21 offset0:2 offset1:3
	ds_write2_b32 v40, v22, v23 offset0:4 offset1:5
	ds_write2_b32 v40, v24, v25 offset0:6 offset1:7
	ds_write2_b32 v40, v26, v27 offset0:8 offset1:9
	ds_write2_b32 v40, v28, v29 offset0:10 offset1:11
	ds_write2_b32 v40, v30, v31 offset0:12 offset1:13
	ds_write2_b32 v40, v32, v33 offset0:14 offset1:15
	s_waitcnt lgkmcnt(0)
	s_mov_b32 exec_lo, vcc_lo
	s_mov_b32 exec_hi, 0
	ds_read2_b32 v[18:19], v40 offset0:0 offset1:1
	ds_read2_b32 v[20:21], v40 offset0:2 offset1:3
	ds_read2_b32 v[22:23], v40 offset0:4 offset1:5
	ds_read2_b32 v[24:25], v40 offset0:6 offset1:7
	ds_read2_b32 v[26:27], v40 offset0:8 offset1:9
	ds_read2_b32 v[28:29], v40 offset0:10 offset1:11
	ds_read2_b32 v[30:31], v40 offset0:12 offset1:13
	ds_read2_b32 v[32:33], v40 offset0:14 offset1:15
	s_waitcnt lgkmcnt(0)
	v_add_f32_e32 v18, v17, v18
	v_fmac_f32_e32 v19, 0.5, v7
	v_add_f32_e32 v20, v15, v20
	v_fmac_f32_e32 v21, 0.5, v8
	v_add_f32_e32 v22, v13, v22
	v_fmac_f32_e32 v23, 0.5, v12
	v_add_f32_e32 v24, v11, v24
	v_fmac_f32_e32 v25, 0.5, v16
	v_add_f32_e32 v26, v9, v26
	v_fmac_f32_e32 v27, 0.5, v6
	v_add_f32_e32 v28, v5, v28
	v_fmac_f32_e32 v29, 0.5, v10
	v_add_f32_e32 v30, v4, v30
	v_fmac_f32_e32 v31, 0.5, v14
	v_add_f32_e32 v32, v3, v32
	v_fmac_f32_e32 v33, 0.5, v2
	ds_write2_b32 v40, v18, v19 offset0:0 offset1:1
	ds_write2_b32 v40, v20, v21 offset0:2 offset1:3
	ds_write2_b32 v40, v22, v23 offset0:4 offset1:5
	ds_write2_b32 v40, v24, v25 offset0:6 offset1:7
	ds_write2_b32 v40, v26, v27 offset0:8 offset1:9
	ds_write2_b32 v40, v28, v29 offset0:10 offset1:11
	ds_write2_b32 v40, v30, v31 offset0:12 offset1:13
	ds_write2_b32 v40, v32, v33 offset0:14 offset1:15
	s_waitcnt lgkmcnt(0)
	s_mov_b64 exec, vcc
	s_branch .LBB0_1473

.LBB0_1554:
	s_or_b64 exec, exec, s[20:21]
	v_add_u32_e32 v9, 0x80, v181
	s_waitcnt lgkmcnt(0)
	v_ashrrev_i32_e32 v1, 31, v10
	v_ashrrev_i32_e32 v7, 31, v8
	v_or_b32_e32 v1, 0x80000000, v1
	v_or_b32_e32 v7, 0x80000000, v7
	v_xor_b32_e32 v3, v10, v1
	v_xor_b32_e32 v5, v8, v7
	v_sub_u32_e32 v2, 0x7f, v146
	v_sub_u32_e32 v4, 0x7f, v148
	v_add_u32_e32 v20, 0xffff0b80, v200
	v_lshlrev_b32_e32 v20, 1, v20
	v_lshl_add_u32 v10, v146, 3, v20
	ds_write_b64 v10, v[2:3]
	ds_write_b64 v10, v[4:5] offset:512
	v_mov_b32_e32 v1, 0
	v_mov_b32_e32 v7, 0
	s_mov_b32 s34, 0
	s_waitcnt lgkmcnt(0)
	s_barrier
.Lrk64_0:
	v_add_u32_e32 v10, s34, v20
	ds_read_b128 v[12:15], v10
	ds_read_b128 v[16:19], v10 offset:16
	s_waitcnt lgkmcnt(1)
	v_cmp_gt_u64_e64 s[20:21], v[12:13], v[2:3]
	v_cmp_gt_u64_e64 s[22:23], v[12:13], v[4:5]
	v_cmp_gt_u64_e64 s[26:27], v[14:15], v[2:3]
	v_cmp_gt_u64_e64 s[28:29], v[14:15], v[4:5]
	v_addc_co_u32_e64 v1, vcc, 0, v1, s[20:21]
	v_addc_co_u32_e64 v7, vcc, 0, v7, s[22:23]
	v_addc_co_u32_e64 v1, vcc, 0, v1, s[26:27]
	v_addc_co_u32_e64 v7, vcc, 0, v7, s[28:29]
	ds_read_b128 v[12:15], v10 offset:32
	s_waitcnt lgkmcnt(1)
	v_cmp_gt_u64_e64 s[20:21], v[16:17], v[2:3]
	v_cmp_gt_u64_e64 s[22:23], v[16:17], v[4:5]
	v_cmp_gt_u64_e64 s[26:27], v[18:19], v[2:3]
	v_cmp_gt_u64_e64 s[28:29], v[18:19], v[4:5]
	v_addc_co_u32_e64 v1, vcc, 0, v1, s[20:21]
	v_addc_co_u32_e64 v7, vcc, 0, v7, s[22:23]
	v_addc_co_u32_e64 v1, vcc, 0, v1, s[26:27]
	v_addc_co_u32_e64 v7, vcc, 0, v7, s[28:29]
	ds_read_b128 v[16:19], v10 offset:48
	s_waitcnt lgkmcnt(1)
	v_cmp_gt_u64_e64 s[20:21], v[12:13], v[2:3]
	v_cmp_gt_u64_e64 s[22:23], v[12:13], v[4:5]
	v_cmp_gt_u64_e64 s[26:27], v[14:15], v[2:3]
	v_cmp_gt_u64_e64 s[28:29], v[14:15], v[4:5]
	v_addc_co_u32_e64 v1, vcc, 0, v1, s[20:21]
	v_addc_co_u32_e64 v7, vcc, 0, v7, s[22:23]
	v_addc_co_u32_e64 v1, vcc, 0, v1, s[26:27]
	v_addc_co_u32_e64 v7, vcc, 0, v7, s[28:29]
	s_waitcnt lgkmcnt(0)
	v_cmp_gt_u64_e64 s[20:21], v[16:17], v[2:3]
	v_cmp_gt_u64_e64 s[22:23], v[16:17], v[4:5]
	v_cmp_gt_u64_e64 s[26:27], v[18:19], v[2:3]
	v_cmp_gt_u64_e64 s[28:29], v[18:19], v[4:5]
	v_addc_co_u32_e64 v1, vcc, 0, v1, s[20:21]
	v_addc_co_u32_e64 v7, vcc, 0, v7, s[22:23]
	v_addc_co_u32_e64 v1, vcc, 0, v1, s[26:27]
	v_addc_co_u32_e64 v7, vcc, 0, v7, s[28:29]
	s_add_i32 s34, s34, 64
	s_cmpk_lg_i32 s34, 0x400
	s_cbranch_scc1 .Lrk64_0
	v_mov_b32_e32 v14, v1
	v_mov_b32_e32 v13, 0
	v_mov_b32_e32 v12, v7
	v_mov_b32_e32 v11, 0
	s_add_u32 s38, s43, s84
	v_add_u32_e32 v1, v14, v13
	v_add_u32_e32 v2, v12, v11
	s_addc_u32 s39, s44, 0
	v_cmp_gt_u32_e64 s[22:23], 16, v1
	v_cmp_gt_u32_e32 vcc, 16, v2
	s_and_saveexec_b64 s[20:21], s[6:7]
	s_cbranch_execz .LBB0_1558
	v_ashrrev_i32_e32 v7, 31, v6
	v_lshl_add_u64 v[6:7], v[6:7], 4, s[38:39]
	v_mov_b32_e32 v2, s22
	v_mov_b32_e32 v3, s23
	v_mov_b32_e32 v4, vcc_lo
	v_mov_b32_e32 v5, vcc_hi
	global_store_dwordx4 v[6:7], v[2:5], off

.LBB0_1566:
	s_or_b64 exec, exec, s[20:21]
	s_waitcnt lgkmcnt(0)
	v_ashrrev_i32_e32 v1, 31, v10
	v_ashrrev_i32_e32 v7, 31, v8
	v_or_b32_e32 v1, 0x80000000, v1
	v_or_b32_e32 v7, 0x80000000, v7
	v_xor_b32_e32 v3, v10, v1
	v_xor_b32_e32 v5, v8, v7
	v_sub_u32_e32 v2, 0x7f, v146
	v_sub_u32_e32 v4, 0x7f, v148
	v_add_u32_e32 v20, 0xffff0b80, v200
	v_lshlrev_b32_e32 v20, 1, v20
	v_lshl_add_u32 v10, v146, 3, v20
	ds_write_b64 v10, v[2:3]
	ds_write_b64 v10, v[4:5] offset:512
	v_mov_b32_e32 v1, 0
	v_mov_b32_e32 v7, 0
	s_mov_b32 s34, 0
	s_waitcnt lgkmcnt(0)
	s_barrier
.Lrk64_1:
	v_add_u32_e32 v10, s34, v20
	ds_read_b128 v[12:15], v10
	ds_read_b128 v[16:19], v10 offset:16
	s_waitcnt lgkmcnt(1)
	v_cmp_gt_u64_e64 s[20:21], v[12:13], v[2:3]
	v_cmp_gt_u64_e64 s[22:23], v[12:13], v[4:5]
	v_cmp_gt_u64_e64 s[26:27], v[14:15], v[2:3]
	v_cmp_gt_u64_e64 s[28:29], v[14:15], v[4:5]
	v_addc_co_u32_e64 v1, vcc, 0, v1, s[20:21]
	v_addc_co_u32_e64 v7, vcc, 0, v7, s[22:23]
	v_addc_co_u32_e64 v1, vcc, 0, v1, s[26:27]
	v_addc_co_u32_e64 v7, vcc, 0, v7, s[28:29]
	ds_read_b128 v[12:15], v10 offset:32
	s_waitcnt lgkmcnt(1)
	v_cmp_gt_u64_e64 s[20:21], v[16:17], v[2:3]
	v_cmp_gt_u64_e64 s[22:23], v[16:17], v[4:5]
	v_cmp_gt_u64_e64 s[26:27], v[18:19], v[2:3]
	v_cmp_gt_u64_e64 s[28:29], v[18:19], v[4:5]
	v_addc_co_u32_e64 v1, vcc, 0, v1, s[20:21]
	v_addc_co_u32_e64 v7, vcc, 0, v7, s[22:23]
	v_addc_co_u32_e64 v1, vcc, 0, v1, s[26:27]
	v_addc_co_u32_e64 v7, vcc, 0, v7, s[28:29]
	ds_read_b128 v[16:19], v10 offset:48
	s_waitcnt lgkmcnt(1)
	v_cmp_gt_u64_e64 s[20:21], v[12:13], v[2:3]
	v_cmp_gt_u64_e64 s[22:23], v[12:13], v[4:5]
	v_cmp_gt_u64_e64 s[26:27], v[14:15], v[2:3]
	v_cmp_gt_u64_e64 s[28:29], v[14:15], v[4:5]
	v_addc_co_u32_e64 v1, vcc, 0, v1, s[20:21]
	v_addc_co_u32_e64 v7, vcc, 0, v7, s[22:23]
	v_addc_co_u32_e64 v1, vcc, 0, v1, s[26:27]
	v_addc_co_u32_e64 v7, vcc, 0, v7, s[28:29]
	s_waitcnt lgkmcnt(0)
	v_cmp_gt_u64_e64 s[20:21], v[16:17], v[2:3]
	v_cmp_gt_u64_e64 s[22:23], v[16:17], v[4:5]
	v_cmp_gt_u64_e64 s[26:27], v[18:19], v[2:3]
	v_cmp_gt_u64_e64 s[28:29], v[18:19], v[4:5]
	v_addc_co_u32_e64 v1, vcc, 0, v1, s[20:21]
	v_addc_co_u32_e64 v7, vcc, 0, v7, s[22:23]
	v_addc_co_u32_e64 v1, vcc, 0, v1, s[26:27]
	v_addc_co_u32_e64 v7, vcc, 0, v7, s[28:29]
	s_add_i32 s34, s34, 64
	s_cmpk_lg_i32 s34, 0x400
	s_cbranch_scc1 .Lrk64_1
	v_mov_b32_e32 v14, v1
	v_mov_b32_e32 v13, 0
	v_mov_b32_e32 v12, v7
	v_mov_b32_e32 v11, 0
	v_add_u32_e32 v1, v14, v13
	v_add_u32_e32 v2, v12, v11
	v_cmp_gt_u32_e64 s[22:23], 16, v1
	v_cmp_gt_u32_e32 vcc, 16, v2
	s_and_saveexec_b64 s[20:21], s[6:7]
	s_cbranch_execz .LBB0_1570
	v_ashrrev_i32_e32 v7, 31, v6
	v_lshl_add_u64 v[6:7], v[6:7], 4, s[38:39]
	v_mov_b32_e32 v2, s22
	v_mov_b32_e32 v3, s23
	v_mov_b32_e32 v4, vcc_lo
	v_mov_b32_e32 v5, vcc_hi
	global_store_dwordx4 v[6:7], v[2:5], off

.LBB0_1638:
	s_or_b64 exec, exec, s[20:21]
	s_waitcnt lgkmcnt(0)
	ds_write2st64_b32 v9, v10, v8 offset0:244 offset1:245
	v_ashrrev_i32_e32 v1, 31, v10
	v_ashrrev_i32_e32 v7, 31, v8
	v_or_b32_e32 v1, 0x80000000, v1
	v_or_b32_e32 v7, 0x80000000, v7
	v_xor_b32_e32 v3, v10, v1
	v_xor_b32_e32 v5, v8, v7
	v_sub_u32_e32 v2, 0x7f, v146
	v_sub_u32_e32 v4, 0x7f, v148
	v_add_u32_e32 v20, 0xffff0b80, v200
	v_lshlrev_b32_e32 v20, 1, v20
	v_lshl_add_u32 v10, v146, 3, v20
	ds_write_b64 v10, v[2:3]
	ds_write_b64 v10, v[4:5] offset:512
	v_mov_b32_e32 v1, 0
	v_mov_b32_e32 v7, 0
	s_mov_b32 s34, 0
	s_waitcnt lgkmcnt(0)
	s_barrier
.Lrk64_7:
	v_add_u32_e32 v10, s34, v20
	ds_read_b128 v[12:15], v10
	ds_read_b128 v[16:19], v10 offset:16
	s_waitcnt lgkmcnt(1)
	v_cmp_gt_u64_e64 s[20:21], v[12:13], v[2:3]
	v_cmp_gt_u64_e64 s[22:23], v[12:13], v[4:5]
	v_cmp_gt_u64_e64 s[26:27], v[14:15], v[2:3]
	v_cmp_gt_u64_e64 s[28:29], v[14:15], v[4:5]
	v_addc_co_u32_e64 v1, vcc, 0, v1, s[20:21]
	v_addc_co_u32_e64 v7, vcc, 0, v7, s[22:23]
	v_addc_co_u32_e64 v1, vcc, 0, v1, s[26:27]
	v_addc_co_u32_e64 v7, vcc, 0, v7, s[28:29]
	ds_read_b128 v[12:15], v10 offset:32
	s_waitcnt lgkmcnt(1)
	v_cmp_gt_u64_e64 s[20:21], v[16:17], v[2:3]
	v_cmp_gt_u64_e64 s[22:23], v[16:17], v[4:5]
	v_cmp_gt_u64_e64 s[26:27], v[18:19], v[2:3]
	v_cmp_gt_u64_e64 s[28:29], v[18:19], v[4:5]
	v_addc_co_u32_e64 v1, vcc, 0, v1, s[20:21]
	v_addc_co_u32_e64 v7, vcc, 0, v7, s[22:23]
	v_addc_co_u32_e64 v1, vcc, 0, v1, s[26:27]
	v_addc_co_u32_e64 v7, vcc, 0, v7, s[28:29]
	ds_read_b128 v[16:19], v10 offset:48
	s_waitcnt lgkmcnt(1)
	v_cmp_gt_u64_e64 s[20:21], v[12:13], v[2:3]
	v_cmp_gt_u64_e64 s[22:23], v[12:13], v[4:5]
	v_cmp_gt_u64_e64 s[26:27], v[14:15], v[2:3]
	v_cmp_gt_u64_e64 s[28:29], v[14:15], v[4:5]
	v_addc_co_u32_e64 v1, vcc, 0, v1, s[20:21]
	v_addc_co_u32_e64 v7, vcc, 0, v7, s[22:23]
	v_addc_co_u32_e64 v1, vcc, 0, v1, s[26:27]
	v_addc_co_u32_e64 v7, vcc, 0, v7, s[28:29]
	s_waitcnt lgkmcnt(0)
	v_cmp_gt_u64_e64 s[20:21], v[16:17], v[2:3]
	v_cmp_gt_u64_e64 s[22:23], v[16:17], v[4:5]
	v_cmp_gt_u64_e64 s[26:27], v[18:19], v[2:3]
	v_cmp_gt_u64_e64 s[28:29], v[18:19], v[4:5]
	v_addc_co_u32_e64 v1, vcc, 0, v1, s[20:21]
	v_addc_co_u32_e64 v7, vcc, 0, v7, s[22:23]
	v_addc_co_u32_e64 v1, vcc, 0, v1, s[26:27]
	v_addc_co_u32_e64 v7, vcc, 0, v7, s[28:29]
	s_add_i32 s34, s34, 64
	s_cmpk_lg_i32 s34, 0x400
	s_cbranch_scc1 .Lrk64_7
	v_mov_b32_e32 v13, v1
	v_mov_b32_e32 v12, 0
	v_mov_b32_e32 v11, v7
	v_mov_b32_e32 v9, 0
	v_add_u32_e32 v1, v13, v12
	v_add_u32_e32 v2, v11, v9
	v_cmp_gt_u32_e64 s[22:23], 16, v1
	v_cmp_gt_u32_e32 vcc, 16, v2
	s_and_saveexec_b64 s[20:21], s[6:7]
	s_cbranch_execz .LBB0_1368
	v_ashrrev_i32_e32 v7, 31, v6
	v_lshl_add_u64 v[6:7], v[6:7], 4, s[38:39]
	v_mov_b32_e32 v2, s22
	v_mov_b32_e32 v3, s23
	v_mov_b32_e32 v4, vcc_lo
	v_mov_b32_e32 v5, vcc_hi
	global_store_dwordx4 v[6:7], v[2:5], off
	s_branch .LBB0_1368

.LBB0_1694:
	s_or_b64 exec, exec, s[0:1]
	s_mov_b64 s[0:1], s[58:59]
	s_waitcnt lgkmcnt(0)
	s_barrier
	.p2align 8
	s_load_dwordx2 s[8:9], s[0:1], 0x10
	s_nop 0
	s_load_dwordx2 s[0:1], s[0:1], 0xe0
	v_mov_b32_e32 v202, v208
	v_mov_b32_e32 v3, v0
	v_bfe_u32 v1, v202, 5, 1
	s_waitcnt lgkmcnt(0)
	s_add_u32 s10, s0, 0x1cae8800
	s_addc_u32 s11, s1, 0
	v_ashrrev_i32_e32 v2, 1, v202
	s_add_u32 s16, s0, 0x105d8800
	v_and_b32_e32 v222, 0xffffffe0, v2
	v_lshlrev_b32_e32 v2, 4, v1
	s_addc_u32 s17, s1, 0
	v_lshl_add_u64 v[2:3], s[0:1], 0, v[2:3]
	s_mov_b64 s[2:3], 0xddd8800
	s_add_u32 s18, s0, 0x115d8800
	v_and_b32_e32 v181, 31, v202
	v_lshlrev_b32_e32 v182, 3, v1
	v_lshl_add_u64 v[184:185], v[2:3], 0, s[2:3]
	s_addc_u32 s19, s1, 0
	v_lshlrev_b32_e32 v180, 2, v1
	v_add_u32_e32 v183, 0x1f41, v222
	s_mov_b32 s20, 0
	s_mov_b32 s6, s92
	s_branch .LBB0_1698

.LBB0_1943:
	s_or_b64 exec, exec, s[0:1]
	s_waitcnt lgkmcnt(0)
	s_barrier
	.p2align 8
	s_mov_b64 s[6:7], 0xd80000
	s_mov_b64 s[4:5], 0x20b68800

.LBB0_2025:
	s_or_b64 exec, exec, s[0:1]
	s_mov_b64 s[4:5], s[58:59]
	v_mov_b32_e32 v22, v208
	v_mov_b32_e32 v1, v208
	v_readlane_b32 s0, v255, 20
	s_waitcnt lgkmcnt(0)
	s_barrier
	.p2align 8
	s_lshl_b32 s0, s0, 1
	v_ashrrev_i32_e32 v1, 6, v1
	v_readlane_b32 s6, v254, 21
	v_readlane_b32 s1, v255, 21
	s_or_b32 s14, s0, 1
	v_add_u32_e32 v94, s6, v1
	s_mul_i32 s0, s14, 0x3000
	s_mov_b32 s1, s85
	v_cmp_gt_i32_e32 vcc, s50, v94
	s_and_saveexec_b64 s[6:7], vcc
	v_readlane_b32 s16, v254, 60
	v_readlane_b32 s17, v254, 61
	s_mov_b64 s[18:19], 0x2000
	s_cbranch_execz .LBB0_2028
	s_load_dwordx4 s[8:11], s[4:5], 0xd8
	v_ashrrev_i32_e32 v95, 31, v94
	v_lshlrev_b32_e32 v1, 2, v22
	v_lshlrev_b64 v[2:3], 13, v[94:95]
	v_and_b32_e32 v24, 0xfc, v1
	s_waitcnt lgkmcnt(0)
	v_lshl_add_u64 v[2:3], s[8:9], 0, v[2:3]
	v_lshlrev_b32_e32 v26, 2, v24
	v_mov_b32_e32 v27, v0
	v_lshl_add_u64 v[2:3], v[2:3], 0, v[26:27]
	s_movk_i32 s12, 0x1000
	s_load_dwordx2 s[4:5], s[4:5], 0x28
	global_load_dwordx4 v[62:65], v[2:3], off
	global_load_dwordx4 v[58:61], v[2:3], off offset:1024
	global_load_dwordx4 v[54:57], v[2:3], off offset:2048
	global_load_dwordx4 v[18:21], v[2:3], off offset:3072
	v_add_co_u32_e32 v2, vcc, s12, v2
	s_lshl_b64 s[12:13], s[0:1], 2
	s_nop 0
	v_addc_co_u32_e32 v3, vcc, 0, v3, vcc
	global_load_dwordx4 v[14:17], v[2:3], off
	global_load_dwordx4 v[10:13], v[2:3], off offset:1024
	global_load_dwordx4 v[6:9], v[2:3], off offset:2048
	s_nop 0
	global_load_dwordx4 v[2:5], v[2:3], off offset:3072
	s_add_u32 s12, s10, s12
	s_addc_u32 s13, s11, s13
	s_add_u32 s12, s12, 0x9aa0000
	s_addc_u32 s13, s13, 0
	s_lshl_b32 s84, s14, 11
	s_lshl_b64 s[14:15], s[84:85], 2
	s_waitcnt lgkmcnt(0)
	s_add_u32 s4, s4, s14
	v_or_b32_e32 v32, 0x400, v24
	s_addc_u32 s5, s5, s15
	v_or_b32_e32 v34, 0x500, v24
	v_lshlrev_b32_e32 v40, 2, v32
	v_mov_b32_e32 v41, v0
	v_or_b32_e32 v36, 0x600, v24
	v_lshl_add_u64 v[68:69], s[4:5], 0, v[40:41]
	v_lshlrev_b32_e32 v40, 2, v34
	v_or_b32_e32 v38, 0x700, v24
	v_lshl_add_u64 v[70:71], s[4:5], 0, v[40:41]
	v_lshlrev_b32_e32 v40, 2, v36
	v_lshl_add_u64 v[72:73], s[4:5], 0, v[40:41]
	v_lshlrev_b32_e32 v40, 2, v38
	v_lshl_add_u64 v[74:75], s[4:5], 0, v[40:41]
	v_lshlrev_b64 v[40:41], 12, v[94:95]
	v_and_b32_e32 v22, 63, v22
	v_cmp_lt_i32_e32 vcc, v216, v217
	v_lshl_or_b32 v40, v22, 3, v40
	v_lshl_add_u64 v[66:67], s[4:5], 0, v[26:27]
	v_cndmask_b32_e32 v1, v215, v216, vcc
	v_or_b32_e32 v26, 0x100, v24
	v_or_b32_e32 v28, 0x200, v24
	v_or_b32_e32 v30, 0x300, v24
	v_lshl_add_u64 v[22:23], s[10:11], 0, v[40:41]
	s_mov_b64 s[4:5], 0x9dd8800
	v_lshlrev_b32_e32 v1, 2, v1
	v_lshl_add_u64 v[76:77], v[22:23], 0, s[4:5]
	s_mov_b64 s[10:11], 0
	v_lshlrev_b32_e32 v78, 2, v24
	v_lshlrev_b32_e32 v80, 2, v32
	v_lshlrev_b32_e32 v82, 2, v34
	v_lshlrev_b32_e32 v84, 2, v36
	v_lshlrev_b32_e32 v86, 2, v38
	v_lshlrev_b32_e32 v88, 2, v26
	v_lshlrev_b32_e32 v90, 2, v28
	v_lshlrev_b32_e32 v92, 2, v30

.LBB0_2080:
	s_or_b64 exec, exec, s[4:5]
	v_readlane_b32 s6, v254, 58
	v_readlane_b32 s7, v254, 59
	s_andn2_b64 vcc, exec, s[6:7]
	v_readlane_b32 s6, v255, 20
	v_readlane_b32 s7, v255, 21
	s_mov_b32 s7, s85
	v_writelane_b32 v255, s6, 20
	s_mov_b64 s[4:5], s[58:59]
	v_mov_b32_e32 v1, v208
	s_waitcnt lgkmcnt(0)
	v_mov_b32_e32 v2, v208
	v_writelane_b32 v255, s7, 21
	s_barrier
	.p2align 8
	s_cbranch_vccnz .LBB0_2112
	s_load_dwordx2 s[12:13], s[4:5], 0xe0
	s_load_dwordx4 s[8:11], s[4:5], 0xc0
	v_readlane_b32 s16, v255, 20
	v_readlane_b32 s17, v255, 21
	s_lshl_b64 s[4:5], s[16:17], 25
	s_waitcnt lgkmcnt(0)
	s_add_u32 s14, s12, s4
	s_addc_u32 s15, s13, s5
	s_add_u32 s24, s14, 0x34a0000
	s_mul_i32 s6, s16, 0x18000
	s_addc_u32 s26, s15, 0
	s_add_u32 s6, s8, s6
	s_addc_u32 s7, s9, 0
	s_lshl_b64 s[4:5], s[16:17], 15
	s_add_u32 s8, s10, s4
	s_addc_u32 s9, s11, s5
	v_and_b32_e32 v1, 63, v1
	s_add_u32 s10, s12, 0x9dd8800
	v_ashrrev_i32_e32 v4, 1, v2
	v_lshlrev_b32_e32 v2, 1, v1
	v_mov_b32_e32 v3, v0
	s_addc_u32 s11, s13, 0
	v_lshl_add_u64 v[2:3], s[12:13], 0, v[2:3]
	s_mov_b64 s[4:5], 0xddd8800
	s_add_u32 s27, s14, 0x34a0080
	v_lshl_add_u64 v[178:179], v[2:3], 0, s[4:5]
	s_addc_u32 s28, s15, 0
	v_lshrrev_b32_e32 v2, 5, v4
	s_movk_i32 s4, 0x4080
	s_add_u32 s12, s12, 0x9dd8880
	v_mul_lo_u32 v2, v2, s4
	v_and_b32_e32 v206, 0xffffffe0, v4
	s_addc_u32 s13, s13, 0
	v_lshl_add_u32 v207, v1, 2, v2
	s_mov_b32 s29, s92
	s_mov_b32 s30, s92
	s_branch .LBB0_2083

.LBB0_2164:
	s_or_b64 exec, exec, s[4:5]
	s_mov_b64 s[4:5], s[58:59]
	s_waitcnt lgkmcnt(0)
	v_mov_b32_e32 v2, v208
	v_mov_b32_e32 v3, v208
	s_and_b64 vcc, exec, s[2:3]
	s_barrier
	.p2align 8
	s_cbranch_vccnz .LBB0_2193
	s_load_dwordx4 s[16:19], s[4:5], 0xd8
	v_readlane_b32 s4, v255, 20
	v_readlane_b32 s5, v255, 21
	v_ashrrev_i32_e32 v3, 1, v3
	v_and_b32_e32 v204, 0xffffffe0, v3
	s_waitcnt lgkmcnt(0)
	s_add_u32 s10, s18, 0xddd8800
	s_addc_u32 s11, s19, 0
	s_lshl_b32 s2, s4, 24
	s_add_u32 s2, s18, s2
	s_addc_u32 s3, s19, 0
	s_add_u32 s22, s2, 0x74a0000
	s_addc_u32 s23, s3, 0
	s_lshl_b64 s[0:1], s[0:1], 2
	s_add_u32 s0, s18, s0
	s_addc_u32 s1, s19, s1
	s_add_u32 s0, s0, 0x9aa0000
	s_addc_u32 s1, s1, 0
	s_lshl_b64 s[2:3], s[4:5], 24
	s_add_u32 s2, s18, s2
	s_addc_u32 s3, s19, s3
	s_add_u32 s24, s2, 0x74a0080
	s_addc_u32 s26, s3, 0
	s_add_u32 s12, s18, 0xddd8880
	s_addc_u32 s13, s19, 0
	v_lshrrev_b32_e32 v3, 5, v3
	s_movk_i32 s2, 0x4080
	v_lshlrev_b32_e32 v1, 1, v2
	s_add_u32 s14, s16, 0xe000
	v_mul_lo_u32 v3, v3, s2
	v_and_b32_e32 v2, 63, v2
	v_and_b32_e32 v1, 0x7e, v1
	s_addc_u32 s15, s17, 0
	v_lshl_add_u32 v205, v2, 3, v3
	v_readlane_b32 s27, v255, 9
	v_readlane_b32 s28, v255, 8
	s_mov_b32 s29, s92
